# hoist rope-key row loads to stage start and q-projection weight loads above the preceding stores; 256-B slack pad keeps downstream code placement fixed
# baseline (speedup 1.0000x reference)
; #define LAS __attribute__((address_space(3)))
; __device__ __forceinline__ float bf_lo(unsigned w) { return __uint_as_float(w << 16); }
; __device__ __forceinline__ float bf_hi(unsigned w) { return __uint_as_float(w & 0xffff0000u); }
; __device__ __forceinline__ void mixer_chunk(KP p, LAS unsigned char* lds, int l, int chunk) {
;     ...
;         for (int half = 0; half < 2; ++half) {
;             f32x4 x[8]; float s[8];
; #pragma unroll
;             for (int i = 0; i < 8; ++i) { const u32x2 v = *(const LAS u32x2*)(CO + (16 * w + 8 * half + i) * YLD + 4 * lane);
;                 x[i] = (f32x4){bf_lo(v.x), bf_hi(v.x), bf_lo(v.y), bf_hi(v.y)}; s[i] = (x[i][0] + x[i][1]) + (x[i][2] + x[i][3]); }
; #pragma unroll
;             for (int o = 1; o < 64; o <<= 1)
; #pragma unroll
;                 for (int i = 0; i < 8; ++i) s[i] += __shfl_xor(s[i], o);
.LBB0_297:
	s_or_b32 s6, s6, s88
	s_mulk_i32 s6, 0x210
	v_cndmask_b32_e64 v50, 0, 1, s[40:41]
	v_add_u32_e32 v110, s6, v0
	v_cmp_ne_u32_e32 vcc, 1, v50
	ds_read2_b64 v[50:53], v110 offset1:66
	v_add_u32_e32 v93, 0x800, v110
	ds_read2_b64 v[66:69], v93 offset0:140 offset1:206
	s_mov_b32 s6, 8
	s_mov_b64 s[40:41], 0
	s_waitcnt lgkmcnt(1)
	v_lshlrev_b32_e32 v65, 16, v51
	v_lshlrev_b32_e32 v64, 16, v50
	v_and_b32_e32 v71, 0xffff0000, v51
	v_and_b32_e32 v70, 0xffff0000, v50
	v_pk_add_f32 v[50:51], v[64:65], v[70:71]
	v_lshlrev_b32_e32 v63, 16, v53
	v_lshlrev_b32_e32 v62, 16, v52
	v_and_b32_e32 v73, 0xffff0000, v53
	v_and_b32_e32 v72, 0xffff0000, v52
	v_add_f32_e32 v104, v50, v51
	v_pk_add_f32 v[50:51], v[62:63], v[72:73]
	s_waitcnt lgkmcnt(0)
	v_and_b32_e32 v103, 0xffff0000, v69
	v_add_f32_e32 v105, v50, v51
	ds_read2_b64 v[50:53], v110 offset0:132 offset1:198
	v_and_b32_e32 v102, 0xffff0000, v68
	s_and_b64 vcc, exec, vcc
	s_waitcnt lgkmcnt(0)
	v_lshlrev_b32_e32 v61, 16, v51
	v_lshlrev_b32_e32 v60, 16, v50
	v_and_b32_e32 v95, 0xffff0000, v51
	v_and_b32_e32 v94, 0xffff0000, v50
	v_pk_add_f32 v[50:51], v[60:61], v[94:95]
	v_lshlrev_b32_e32 v59, 16, v53
	v_lshlrev_b32_e32 v58, 16, v52
	v_and_b32_e32 v97, 0xffff0000, v53
	v_and_b32_e32 v96, 0xffff0000, v52
	v_add_f32_e32 v106, v50, v51
	v_pk_add_f32 v[50:51], v[58:59], v[96:97]
	s_nop 0
	v_add_f32_e32 v107, v50, v51
	ds_read2_b64 v[50:53], v93 offset0:8 offset1:74
	s_waitcnt lgkmcnt(0)
	v_lshlrev_b32_e32 v57, 16, v51
	v_lshlrev_b32_e32 v56, 16, v50
	v_and_b32_e32 v99, 0xffff0000, v51
	v_and_b32_e32 v98, 0xffff0000, v50
	v_pk_add_f32 v[50:51], v[56:57], v[98:99]
	v_lshlrev_b32_e32 v55, 16, v53
	v_lshlrev_b32_e32 v54, 16, v52
	v_and_b32_e32 v101, 0xffff0000, v53
	v_and_b32_e32 v100, 0xffff0000, v52
	v_add_f32_e32 v108, v50, v51
	v_pk_add_f32 v[50:51], v[54:55], v[100:101]
	v_lshlrev_b32_e32 v53, 16, v67
	v_lshlrev_b32_e32 v52, 16, v66
	v_and_b32_e32 v67, 0xffff0000, v67
	v_and_b32_e32 v66, 0xffff0000, v66
	v_add_f32_e32 v109, v50, v51
	v_pk_add_f32 v[50:51], v[52:53], v[66:67]
	s_nop 0
	v_add_f32_e32 v111, v50, v51
	v_lshlrev_b32_e32 v51, 16, v69
	v_lshlrev_b32_e32 v50, 16, v68
	v_pk_add_f32 v[68:69], v[50:51], v[102:103]
	s_nop 0
	v_add_f32_e32 v68, v68, v69
	ds_bpermute_b32 v69, v213, v104
	s_waitcnt lgkmcnt(0)
	v_add_f32_e32 v69, v104, v69
	ds_bpermute_b32 v104, v213, v105
	s_waitcnt lgkmcnt(0)
	v_add_f32_e32 v104, v105, v104
	ds_bpermute_b32 v105, v213, v106
	s_waitcnt lgkmcnt(0)
	v_add_f32_e32 v105, v106, v105
	ds_bpermute_b32 v106, v213, v107
	s_waitcnt lgkmcnt(0)
	v_add_f32_e32 v106, v107, v106
	ds_bpermute_b32 v107, v213, v108
	s_waitcnt lgkmcnt(0)
	v_add_f32_e32 v107, v108, v107
	ds_bpermute_b32 v108, v213, v109
	s_waitcnt lgkmcnt(0)
	v_add_f32_e32 v108, v109, v108
	ds_bpermute_b32 v109, v213, v111
	s_waitcnt lgkmcnt(0)
	v_add_f32_e32 v109, v111, v109
	ds_bpermute_b32 v111, v213, v68
	s_waitcnt lgkmcnt(0)
	v_add_f32_e32 v68, v68, v111
	ds_bpermute_b32 v111, v214, v69
	s_waitcnt lgkmcnt(0)
	v_add_f32_e32 v69, v69, v111
	ds_bpermute_b32 v111, v214, v104
	s_waitcnt lgkmcnt(0)
	v_add_f32_e32 v104, v104, v111
	ds_bpermute_b32 v111, v214, v105
	s_waitcnt lgkmcnt(0)
	v_add_f32_e32 v105, v105, v111
	ds_bpermute_b32 v111, v214, v106
	s_waitcnt lgkmcnt(0)
	v_add_f32_e32 v106, v106, v111
	ds_bpermute_b32 v111, v214, v107
	s_waitcnt lgkmcnt(0)
	v_add_f32_e32 v107, v107, v111
	ds_bpermute_b32 v111, v214, v108
	s_waitcnt lgkmcnt(0)
	v_add_f32_e32 v108, v108, v111
	ds_bpermute_b32 v111, v214, v109
	s_waitcnt lgkmcnt(0)
	v_add_f32_e32 v109, v109, v111
	ds_bpermute_b32 v111, v214, v68
	s_waitcnt lgkmcnt(0)
	v_add_f32_e32 v68, v68, v111
	ds_bpermute_b32 v111, v91, v69
	s_waitcnt lgkmcnt(0)
	v_add_f32_e32 v69, v69, v111
	ds_bpermute_b32 v111, v91, v104
	s_waitcnt lgkmcnt(0)
	v_add_f32_e32 v104, v104, v111
	ds_bpermute_b32 v111, v91, v105
	s_waitcnt lgkmcnt(0)
	v_add_f32_e32 v105, v105, v111
	ds_bpermute_b32 v111, v91, v106
	s_waitcnt lgkmcnt(0)
	v_add_f32_e32 v106, v106, v111
	ds_bpermute_b32 v111, v91, v107
	s_waitcnt lgkmcnt(0)
	v_add_f32_e32 v107, v107, v111
	ds_bpermute_b32 v111, v91, v108
	s_waitcnt lgkmcnt(0)
	v_add_f32_e32 v108, v108, v111
	ds_bpermute_b32 v111, v91, v109
	s_waitcnt lgkmcnt(0)
	v_add_f32_e32 v109, v109, v111
	ds_bpermute_b32 v111, v91, v68
	s_waitcnt lgkmcnt(0)
	v_add_f32_e32 v68, v68, v111
	ds_bpermute_b32 v111, v92, v69
	s_waitcnt lgkmcnt(0)
	v_add_f32_e32 v69, v69, v111
	ds_bpermute_b32 v111, v92, v104
	s_waitcnt lgkmcnt(0)
	v_add_f32_e32 v104, v104, v111
	ds_bpermute_b32 v111, v92, v105
	s_waitcnt lgkmcnt(0)
	v_add_f32_e32 v105, v105, v111
	ds_bpermute_b32 v111, v92, v106
	s_waitcnt lgkmcnt(0)
	v_add_f32_e32 v106, v106, v111
	ds_bpermute_b32 v111, v92, v107
	s_waitcnt lgkmcnt(0)
	v_add_f32_e32 v107, v107, v111
	ds_bpermute_b32 v111, v92, v108
	s_waitcnt lgkmcnt(0)
	v_add_f32_e32 v108, v108, v111
	ds_bpermute_b32 v111, v92, v109
	s_waitcnt lgkmcnt(0)
	v_add_f32_e32 v109, v109, v111
	ds_bpermute_b32 v111, v92, v68
	s_waitcnt lgkmcnt(0)
	v_add_f32_e32 v68, v68, v111
	ds_bpermute_b32 v111, v207, v69
	s_waitcnt lgkmcnt(0)
	v_add_f32_e32 v69, v69, v111
	ds_bpermute_b32 v111, v207, v104
	s_waitcnt lgkmcnt(0)
	v_add_f32_e32 v104, v104, v111
	ds_bpermute_b32 v111, v207, v105
	s_waitcnt lgkmcnt(0)
	v_add_f32_e32 v105, v105, v111
	ds_bpermute_b32 v111, v207, v106
	s_waitcnt lgkmcnt(0)
	v_add_f32_e32 v106, v106, v111
	ds_bpermute_b32 v111, v207, v107
	s_waitcnt lgkmcnt(0)
	v_add_f32_e32 v107, v107, v111
	ds_bpermute_b32 v111, v207, v108
	s_waitcnt lgkmcnt(0)
	v_add_f32_e32 v108, v108, v111
	ds_bpermute_b32 v111, v207, v109
	s_waitcnt lgkmcnt(0)
	v_add_f32_e32 v109, v109, v111
	ds_bpermute_b32 v111, v207, v68
	s_waitcnt lgkmcnt(0)
; #define LAS __attribute__((address_space(3)))
; __device__ __forceinline__ float bf_lo(unsigned w) { return __uint_as_float(w << 16); }
; __device__ __forceinline__ float bf_hi(unsigned w) { return __uint_as_float(w & 0xffff0000u); }
; __device__ __forceinline__ void mixer_chunk(KP p, LAS unsigned char* lds, int l, int chunk) {
;     ...
;             for (int i = 0; i < 8; ++i) { const u32x2 v = *(const LAS u32x2*)(CO + (16 * w + 8 * half + i) * YLD + 4 * lane);
;                 x[i] = (f32x4){bf_lo(v.x), bf_hi(v.x), bf_lo(v.y), bf_hi(v.y)}; s[i] = (x[i][0] + x[i][1]) + (x[i][2] + x[i][3]); }
; #pragma unroll
;             for (int o = 1; o < 64; o <<= 1)
; #pragma unroll
;                 for (int i = 0; i < 8; ++i) s[i] += __shfl_xor(s[i], o);
; #pragma unroll
;             for (int i = 0; i < 8; ++i) { x[i] = x[i] - s[i] * (1.0f / 256.0f); s[i] = (x[i][0] * x[i][0] + x[i][1] * x[i][1]) + (x[i][2] * x[i][2] + x[i][3] * x[i][3]); }
; #pragma unroll
;             for (int o = 1; o < 64; o <<= 1)
; #pragma unroll
;                 for (int i = 0; i < 8; ++i) s[i] += __shfl_xor(s[i], o);
	v_add_f32_e32 v68, v68, v111
	ds_bpermute_b32 v111, v208, v69
	s_waitcnt lgkmcnt(0)
	v_add_f32_e32 v69, v69, v111
	ds_bpermute_b32 v111, v208, v104
	v_fmac_f32_e32 v70, 0xbb800000, v69
	v_fmac_f32_e32 v71, 0xbb800000, v69
	v_fmac_f32_e32 v65, 0xbb800000, v69
	v_fmac_f32_e32 v64, 0xbb800000, v69
	s_waitcnt lgkmcnt(0)
	v_add_f32_e32 v111, v104, v111
	ds_bpermute_b32 v104, v208, v105
	v_fmac_f32_e32 v72, 0xbb800000, v111
	v_fmac_f32_e32 v73, 0xbb800000, v111
	v_fmac_f32_e32 v63, 0xbb800000, v111
	v_fmac_f32_e32 v62, 0xbb800000, v111
	s_waitcnt lgkmcnt(0)
	v_add_f32_e32 v112, v105, v104
	ds_bpermute_b32 v104, v208, v106
	v_mov_b32_e32 v105, v71
	v_fmac_f32_e32 v94, 0xbb800000, v112
	v_fmac_f32_e32 v95, 0xbb800000, v112
	v_fmac_f32_e32 v61, 0xbb800000, v112
	s_waitcnt lgkmcnt(0)
	v_add_f32_e32 v113, v106, v104
	ds_bpermute_b32 v104, v208, v107
	v_fmac_f32_e32 v60, 0xbb800000, v112
	v_fmac_f32_e32 v96, 0xbb800000, v113
	v_fmac_f32_e32 v97, 0xbb800000, v113
	v_fmac_f32_e32 v59, 0xbb800000, v113
	s_waitcnt lgkmcnt(0)
	v_add_f32_e32 v114, v107, v104
	ds_bpermute_b32 v104, v208, v108
	v_fmac_f32_e32 v58, 0xbb800000, v113
	v_fmac_f32_e32 v98, 0xbb800000, v114
	v_fmac_f32_e32 v99, 0xbb800000, v114
	v_fmac_f32_e32 v57, 0xbb800000, v114
	s_waitcnt lgkmcnt(0)
	v_add_f32_e32 v115, v108, v104
	ds_bpermute_b32 v104, v208, v109
	v_mov_b32_e32 v108, v61
	v_mov_b32_e32 v61, v94
	v_mov_b32_e32 v94, v59
	v_mov_b32_e32 v59, v96
	s_waitcnt lgkmcnt(0)
	v_add_f32_e32 v116, v109, v104
	ds_bpermute_b32 v104, v208, v68
	v_mov_b32_e32 v109, v95
	v_mov_b32_e32 v95, v97
	v_fmac_f32_e32 v56, 0xbb800000, v114
	v_fmac_f32_e32 v100, 0xbb800000, v115
	s_waitcnt lgkmcnt(0)
	v_add_f32_e32 v117, v68, v104
	v_mov_b32_e32 v104, v65
	v_mov_b32_e32 v65, v70
	v_pk_mul_f32 v[68:69], v[104:105], v[104:105]
	v_pk_mul_f32 v[70:71], v[64:65], v[64:65]
	v_fmac_f32_e32 v101, 0xbb800000, v115
	v_pk_mov_b32 v[106:107], v[70:71], v[68:69] op_sel:[1,0]
	v_mov_b32_e32 v71, v69
	v_pk_add_f32 v[68:69], v[106:107], v[70:71]
	v_mov_b32_e32 v106, v63
	v_mov_b32_e32 v107, v73
	v_mov_b32_e32 v63, v72
	v_add_f32_e32 v118, v68, v69
	v_pk_mul_f32 v[68:69], v[106:107], v[106:107]
	v_pk_mul_f32 v[70:71], v[62:63], v[62:63]
	v_fmac_f32_e32 v55, 0xbb800000, v115
	v_pk_mov_b32 v[72:73], v[70:71], v[68:69] op_sel:[1,0]
	v_mov_b32_e32 v71, v69
	v_pk_add_f32 v[68:69], v[72:73], v[70:71]
	v_pk_mul_f32 v[70:71], v[60:61], v[60:61]
	v_add_f32_e32 v111, v68, v69
	v_pk_mul_f32 v[68:69], v[108:109], v[108:109]
	v_fmac_f32_e32 v54, 0xbb800000, v115
	v_pk_mov_b32 v[72:73], v[70:71], v[68:69] op_sel:[1,0]
	v_mov_b32_e32 v71, v69
	v_pk_add_f32 v[68:69], v[72:73], v[70:71]
	v_pk_mul_f32 v[70:71], v[58:59], v[58:59]
	v_add_f32_e32 v112, v68, v69
	v_pk_mul_f32 v[68:69], v[94:95], v[94:95]
	v_fmac_f32_e32 v66, 0xbb800000, v116
	v_pk_mov_b32 v[72:73], v[70:71], v[68:69] op_sel:[1,0]
	v_mov_b32_e32 v71, v69
	v_pk_add_f32 v[68:69], v[72:73], v[70:71]
	v_mov_b32_e32 v72, v57
	v_mov_b32_e32 v73, v99
	v_mov_b32_e32 v57, v98
	v_add_f32_e32 v113, v68, v69
	v_pk_mul_f32 v[68:69], v[72:73], v[72:73]
	v_pk_mul_f32 v[70:71], v[56:57], v[56:57]
	v_fmac_f32_e32 v67, 0xbb800000, v116
	v_pk_mov_b32 v[96:97], v[70:71], v[68:69] op_sel:[1,0]
	v_mov_b32_e32 v71, v69
	v_pk_add_f32 v[68:69], v[96:97], v[70:71]
	v_mov_b32_e32 v70, v55
	v_mov_b32_e32 v71, v101
	v_mov_b32_e32 v55, v100
	v_add_f32_e32 v114, v68, v69
	v_pk_mul_f32 v[68:69], v[70:71], v[70:71]
	v_pk_mul_f32 v[96:97], v[54:55], v[54:55]
	v_fmac_f32_e32 v53, 0xbb800000, v116
	v_pk_mov_b32 v[98:99], v[96:97], v[68:69] op_sel:[1,0]
	v_mov_b32_e32 v97, v69
	v_pk_add_f32 v[68:69], v[98:99], v[96:97]
	v_fmac_f32_e32 v52, 0xbb800000, v116
	v_add_f32_e32 v115, v68, v69
	v_mov_b32_e32 v68, v53
	v_mov_b32_e32 v69, v67
	v_mov_b32_e32 v53, v66
	v_pk_mul_f32 v[96:97], v[68:69], v[68:69]
	v_pk_mul_f32 v[66:67], v[52:53], v[52:53]
	v_fmac_f32_e32 v102, 0xbb800000, v117
	v_pk_mov_b32 v[98:99], v[66:67], v[96:97] op_sel:[1,0]
	v_mov_b32_e32 v67, v97
	v_pk_add_f32 v[66:67], v[98:99], v[66:67]
	v_fmac_f32_e32 v103, 0xbb800000, v117
	v_fmac_f32_e32 v51, 0xbb800000, v117
	v_add_f32_e32 v116, v66, v67
	v_fmac_f32_e32 v50, 0xbb800000, v117
	v_mov_b32_e32 v66, v51
	v_mov_b32_e32 v67, v103
	v_mov_b32_e32 v51, v102
	v_pk_mul_f32 v[96:97], v[66:67], v[66:67]
	v_pk_mul_f32 v[98:99], v[50:51], v[50:51]
	ds_bpermute_b32 v102, v213, v115
	v_pk_mov_b32 v[100:101], v[98:99], v[96:97] op_sel:[1,0]
	v_mov_b32_e32 v99, v97
	v_pk_add_f32 v[96:97], v[100:101], v[98:99]
	ds_bpermute_b32 v98, v213, v111
	v_add_f32_e32 v96, v96, v97
	ds_bpermute_b32 v97, v213, v118
	ds_bpermute_b32 v99, v213, v112
	ds_bpermute_b32 v100, v213, v113
	s_waitcnt lgkmcnt(3)
	v_add_f32_e32 v98, v111, v98
	ds_bpermute_b32 v111, v213, v96
	s_waitcnt lgkmcnt(3)
	v_add_f32_e32 v97, v118, v97
	s_waitcnt lgkmcnt(2)
	v_add_f32_e32 v99, v112, v99
	s_waitcnt lgkmcnt(1)
	v_add_f32_e32 v100, v113, v100
	ds_bpermute_b32 v101, v213, v114
	s_waitcnt lgkmcnt(1)
	v_add_f32_e32 v96, v96, v111
	ds_bpermute_b32 v111, v214, v97
	v_add_f32_e32 v102, v115, v102
	ds_bpermute_b32 v103, v213, v116
	s_waitcnt lgkmcnt(2)
	v_add_f32_e32 v101, v114, v101
	s_waitcnt lgkmcnt(1)
	v_add_f32_e32 v97, v97, v111
	ds_bpermute_b32 v111, v214, v98
	s_waitcnt lgkmcnt(1)
	v_add_f32_e32 v103, v116, v103
	s_waitcnt lgkmcnt(0)
	v_add_f32_e32 v98, v98, v111
	ds_bpermute_b32 v111, v214, v99
	s_waitcnt lgkmcnt(0)
	v_add_f32_e32 v99, v99, v111
	ds_bpermute_b32 v111, v214, v100
	s_waitcnt lgkmcnt(0)
	v_add_f32_e32 v100, v100, v111
	ds_bpermute_b32 v111, v214, v101
	s_waitcnt lgkmcnt(0)
	v_add_f32_e32 v101, v101, v111
	ds_bpermute_b32 v111, v214, v102
	s_waitcnt lgkmcnt(0)
; #define LAS __attribute__((address_space(3)))
; __device__ __forceinline__ unsigned pk2(float lo, float hi) { unsigned r; asm("v_cvt_pk_bf16_f32 %0, %1, %2" : "=v"(r) : "v"(lo), "v"(hi)); return r; }
; __device__ __forceinline__ float sigmoidf_(float x) { return fast_rcp(1.0f + fast_exp2(-1.4426950408889634f * x)); }
; __device__ __forceinline__ float rsq(float x) { return __builtin_amdgcn_rsqf(x); }
; __device__ __forceinline__ void mixer_chunk(KP p, LAS unsigned char* lds, int l, int chunk) {
;     ...
;             for (int o = 1; o < 64; o <<= 1)
; #pragma unroll
;                 for (int i = 0; i < 8; ++i) s[i] += __shfl_xor(s[i], o);
; #pragma unroll
;             for (int i = 0; i < 8; ++i) { x[i] = x[i] - s[i] * (1.0f / 256.0f); s[i] = (x[i][0] * x[i][0] + x[i][1] * x[i][1]) + (x[i][2] * x[i][2] + x[i][3] * x[i][3]); }
; #pragma unroll
;             for (int o = 1; o < 64; o <<= 1)
; #pragma unroll
;                 for (int i = 0; i < 8; ++i) s[i] += __shfl_xor(s[i], o);
; #pragma unroll
;             for (int i = 0; i < 8; ++i) {
;                 const float rstd = rsq(s[i] * (1.0f / 256.0f) + EPS);
;                 f32x4 y = x[i] * rstd * lg + lb;
; #pragma unroll
;                 for (int j = 0; j < 4; ++j) y[j] = y[j] * sigmoidf_(y[j]);
;                 u32x2 o; o.x = pk2(y[0], y[1]); o.y = pk2(y[2], y[3]); *(LAS u32x2*)(CO + (16 * w + 8 * half + i) * YLD + 4 * lane) = o;
	v_add_f32_e32 v102, v102, v111
	ds_bpermute_b32 v111, v214, v103
	s_waitcnt lgkmcnt(0)
	v_add_f32_e32 v103, v103, v111
	ds_bpermute_b32 v111, v214, v96
	s_waitcnt lgkmcnt(0)
	v_add_f32_e32 v96, v96, v111
	ds_bpermute_b32 v111, v91, v97
	s_waitcnt lgkmcnt(0)
	v_add_f32_e32 v97, v97, v111
	ds_bpermute_b32 v111, v91, v98
	s_waitcnt lgkmcnt(0)
	v_add_f32_e32 v98, v98, v111
	ds_bpermute_b32 v111, v91, v99
	s_waitcnt lgkmcnt(0)
	v_add_f32_e32 v99, v99, v111
	ds_bpermute_b32 v111, v91, v100
	s_waitcnt lgkmcnt(0)
	v_add_f32_e32 v100, v100, v111
	ds_bpermute_b32 v111, v91, v101
	s_waitcnt lgkmcnt(0)
	v_add_f32_e32 v101, v101, v111
	ds_bpermute_b32 v111, v91, v102
	s_waitcnt lgkmcnt(0)
	v_add_f32_e32 v102, v102, v111
	ds_bpermute_b32 v111, v91, v103
	s_waitcnt lgkmcnt(0)
	v_add_f32_e32 v103, v103, v111
	ds_bpermute_b32 v111, v91, v96
	s_waitcnt lgkmcnt(0)
	v_add_f32_e32 v96, v96, v111
	ds_bpermute_b32 v111, v92, v97
	s_waitcnt lgkmcnt(0)
	v_add_f32_e32 v97, v97, v111
	ds_bpermute_b32 v111, v92, v98
	s_waitcnt lgkmcnt(0)
	v_add_f32_e32 v98, v98, v111
	ds_bpermute_b32 v111, v92, v99
	s_waitcnt lgkmcnt(0)
	v_add_f32_e32 v99, v99, v111
	ds_bpermute_b32 v111, v92, v100
	s_waitcnt lgkmcnt(0)
	v_add_f32_e32 v100, v100, v111
	ds_bpermute_b32 v111, v92, v101
	s_waitcnt lgkmcnt(0)
	v_add_f32_e32 v101, v101, v111
	ds_bpermute_b32 v111, v92, v102
	s_waitcnt lgkmcnt(0)
	v_add_f32_e32 v102, v102, v111
	ds_bpermute_b32 v111, v92, v103
	s_waitcnt lgkmcnt(0)
	v_add_f32_e32 v103, v103, v111
	ds_bpermute_b32 v111, v92, v96
	s_waitcnt lgkmcnt(0)
	v_add_f32_e32 v96, v96, v111
	ds_bpermute_b32 v111, v207, v97
	s_waitcnt lgkmcnt(0)
	v_add_f32_e32 v97, v97, v111
	ds_bpermute_b32 v111, v207, v98
	s_waitcnt lgkmcnt(0)
	v_add_f32_e32 v98, v98, v111
	ds_bpermute_b32 v111, v207, v99
	s_waitcnt lgkmcnt(0)
	v_add_f32_e32 v99, v99, v111
	ds_bpermute_b32 v111, v207, v100
	s_waitcnt lgkmcnt(0)
	v_add_f32_e32 v100, v100, v111
	ds_bpermute_b32 v111, v207, v101
	s_waitcnt lgkmcnt(0)
	v_add_f32_e32 v101, v101, v111
	ds_bpermute_b32 v111, v207, v102
	s_waitcnt lgkmcnt(0)
	v_add_f32_e32 v102, v102, v111
	ds_bpermute_b32 v111, v207, v103
	s_waitcnt lgkmcnt(0)
	v_add_f32_e32 v103, v103, v111
	ds_bpermute_b32 v111, v207, v96
	s_waitcnt lgkmcnt(0)
	v_add_f32_e32 v96, v96, v111
	ds_bpermute_b32 v111, v208, v97
	s_waitcnt lgkmcnt(0)
	v_add_f32_e32 v97, v97, v111
	ds_bpermute_b32 v111, v208, v98
	s_waitcnt lgkmcnt(0)
	v_add_f32_e32 v98, v98, v111
	ds_bpermute_b32 v111, v208, v99
	s_waitcnt lgkmcnt(0)
	v_add_f32_e32 v99, v99, v111
	ds_bpermute_b32 v111, v208, v100
	s_waitcnt lgkmcnt(0)
	v_add_f32_e32 v100, v100, v111
	ds_bpermute_b32 v111, v208, v101
	s_waitcnt lgkmcnt(0)
	v_add_f32_e32 v101, v101, v111
	ds_bpermute_b32 v111, v208, v102
	s_waitcnt lgkmcnt(0)
	v_add_f32_e32 v102, v102, v111
	ds_bpermute_b32 v111, v208, v103
	s_waitcnt lgkmcnt(0)
	v_add_f32_e32 v103, v103, v111
	ds_bpermute_b32 v111, v208, v96
	s_waitcnt lgkmcnt(0)
	v_add_f32_e32 v111, v96, v111
	v_fmamk_f32 v96, v97, 0x3b800000, v189
	v_rsq_f32_e32 v96, v96
	s_nop 0
	v_pk_mul_f32 v[64:65], v[64:65], v[96:97] op_sel_hi:[1,0]
	s_waitcnt vmcnt(1)
	v_pk_fma_f32 v[64:65], v[42:43], v[64:65], v[46:47]
	v_pk_mul_f32 v[96:97], v[104:105], v[96:97] op_sel_hi:[1,0]
	v_mul_f32_e32 v104, 0xbfb8aa3b, v64
	v_exp_f32_e32 v104, v104
	v_pk_fma_f32 v[96:97], v[44:45], v[96:97], v[48:49]
	v_add_f32_e32 v104, 1.0, v104
	v_rcp_f32_e32 v104, v104
	s_nop 0
	v_mul_f32_e32 v64, v64, v104
	v_mul_f32_e32 v104, 0xbfb8aa3b, v65
	v_exp_f32_e32 v104, v104
	s_nop 0
	v_add_f32_e32 v104, 1.0, v104
	v_rcp_f32_e32 v104, v104
	s_nop 0
	v_mul_f32_e32 v65, v65, v104
	v_mul_f32_e32 v104, 0xbfb8aa3b, v96
	v_exp_f32_e32 v104, v104
	v_cvt_pk_bf16_f32 v64, v64, v65
	s_nop 0
	v_add_f32_e32 v104, 1.0, v104
	v_rcp_f32_e32 v104, v104
	s_nop 0
	v_mul_f32_e32 v96, v96, v104
	v_mul_f32_e32 v104, 0xbfb8aa3b, v97
	v_exp_f32_e32 v104, v104
	s_nop 0
	v_add_f32_e32 v104, 1.0, v104
	v_rcp_f32_e32 v104, v104
	s_nop 0
	v_mul_f32_e32 v97, v97, v104
	v_cvt_pk_bf16_f32 v65, v96, v97
	v_fmamk_f32 v96, v98, 0x3b800000, v189
	v_rsq_f32_e32 v96, v96
	s_nop 0
	v_pk_mul_f32 v[62:63], v[62:63], v[96:97] op_sel_hi:[1,0]
	s_nop 0
	v_pk_fma_f32 v[62:63], v[42:43], v[62:63], v[46:47]
	v_pk_mul_f32 v[96:97], v[106:107], v[96:97] op_sel_hi:[1,0]
	v_mul_f32_e32 v98, 0xbfb8aa3b, v62
	v_exp_f32_e32 v98, v98
	v_pk_fma_f32 v[96:97], v[44:45], v[96:97], v[48:49]
	v_add_f32_e32 v98, 1.0, v98
	v_rcp_f32_e32 v98, v98
	s_nop 0
	v_mul_f32_e32 v62, v62, v98
	v_mul_f32_e32 v98, 0xbfb8aa3b, v63
	v_exp_f32_e32 v98, v98
	s_nop 0
	v_add_f32_e32 v98, 1.0, v98
	v_rcp_f32_e32 v98, v98
	s_nop 0
	v_mul_f32_e32 v63, v63, v98
	v_mul_f32_e32 v98, 0xbfb8aa3b, v96
	v_exp_f32_e32 v98, v98
	v_cvt_pk_bf16_f32 v62, v62, v63
	s_nop 0
	v_add_f32_e32 v98, 1.0, v98
	v_rcp_f32_e32 v98, v98
	s_nop 0
	v_mul_f32_e32 v96, v96, v98
	v_mul_f32_e32 v98, 0xbfb8aa3b, v97
	v_exp_f32_e32 v98, v98
	s_nop 0
	v_add_f32_e32 v98, 1.0, v98
	v_rcp_f32_e32 v98, v98
	s_nop 0
	v_mul_f32_e32 v97, v97, v98
	v_cvt_pk_bf16_f32 v63, v96, v97
	ds_write2_b64 v110, v[64:65], v[62:63] offset1:66
	v_fmamk_f32 v62, v99, 0x3b800000, v189
	v_rsq_f32_e32 v62, v62
	s_nop 0
	v_pk_mul_f32 v[60:61], v[60:61], v[62:63] op_sel_hi:[1,0]
	s_nop 0
	v_pk_fma_f32 v[60:61], v[42:43], v[60:61], v[46:47]
	v_pk_mul_f32 v[62:63], v[108:109], v[62:63] op_sel_hi:[1,0]
	v_mul_f32_e32 v64, 0xbfb8aa3b, v60
	v_exp_f32_e32 v64, v64
	v_pk_fma_f32 v[62:63], v[44:45], v[62:63], v[48:49]
	v_add_f32_e32 v64, 1.0, v64
	v_rcp_f32_e32 v64, v64
	s_nop 0
	v_mul_f32_e32 v60, v60, v64
	v_mul_f32_e32 v64, 0xbfb8aa3b, v61
	v_exp_f32_e32 v64, v64
	s_nop 0
	v_add_f32_e32 v64, 1.0, v64
	v_rcp_f32_e32 v64, v64
; #define LAS __attribute__((address_space(3)))
; __device__ __forceinline__ unsigned pk2(float lo, float hi) { unsigned r; asm("v_cvt_pk_bf16_f32 %0, %1, %2" : "=v"(r) : "v"(lo), "v"(hi)); return r; }
; __device__ __forceinline__ float sigmoidf_(float x) { return fast_rcp(1.0f + fast_exp2(-1.4426950408889634f * x)); }
; __device__ __forceinline__ float rsq(float x) { return __builtin_amdgcn_rsqf(x); }
; __device__ __forceinline__ void mixer_chunk(KP p, LAS unsigned char* lds, int l, int chunk) {
;     ...
;             for (int i = 0; i < 8; ++i) {
;                 const float rstd = rsq(s[i] * (1.0f / 256.0f) + EPS);
;                 f32x4 y = x[i] * rstd * lg + lb;
; #pragma unroll
;                 for (int j = 0; j < 4; ++j) y[j] = y[j] * sigmoidf_(y[j]);
;                 u32x2 o; o.x = pk2(y[0], y[1]); o.y = pk2(y[2], y[3]); *(LAS u32x2*)(CO + (16 * w + 8 * half + i) * YLD + 4 * lane) = o;
;             }
;         }
	s_nop 0
	v_mul_f32_e32 v61, v61, v64
	v_mul_f32_e32 v64, 0xbfb8aa3b, v62
	v_exp_f32_e32 v64, v64
	v_cvt_pk_bf16_f32 v60, v60, v61
	s_nop 0
	v_add_f32_e32 v64, 1.0, v64
	v_rcp_f32_e32 v64, v64
	s_nop 0
	v_mul_f32_e32 v62, v62, v64
	v_mul_f32_e32 v64, 0xbfb8aa3b, v63
	v_exp_f32_e32 v64, v64
	s_nop 0
	v_add_f32_e32 v64, 1.0, v64
	v_rcp_f32_e32 v64, v64
	s_nop 0
	v_mul_f32_e32 v63, v63, v64
	v_cvt_pk_bf16_f32 v61, v62, v63
	v_fmamk_f32 v62, v100, 0x3b800000, v189
	v_rsq_f32_e32 v62, v62
	s_nop 0
	v_pk_mul_f32 v[58:59], v[58:59], v[62:63] op_sel_hi:[1,0]
	s_nop 0
	v_pk_fma_f32 v[58:59], v[42:43], v[58:59], v[46:47]
	v_pk_mul_f32 v[62:63], v[94:95], v[62:63] op_sel_hi:[1,0]
	v_mul_f32_e32 v64, 0xbfb8aa3b, v58
	v_exp_f32_e32 v64, v64
	v_pk_fma_f32 v[62:63], v[44:45], v[62:63], v[48:49]
	v_add_f32_e32 v64, 1.0, v64
	v_rcp_f32_e32 v64, v64
	s_nop 0
	v_mul_f32_e32 v58, v58, v64
	v_mul_f32_e32 v64, 0xbfb8aa3b, v59
	v_exp_f32_e32 v64, v64
	s_nop 0
	v_add_f32_e32 v64, 1.0, v64
	v_rcp_f32_e32 v64, v64
	s_nop 0
	v_mul_f32_e32 v59, v59, v64
	v_mul_f32_e32 v64, 0xbfb8aa3b, v62
	v_exp_f32_e32 v64, v64
	v_cvt_pk_bf16_f32 v58, v58, v59
	s_nop 0
	v_add_f32_e32 v64, 1.0, v64
	v_rcp_f32_e32 v64, v64
	s_nop 0
	v_mul_f32_e32 v62, v62, v64
	v_mul_f32_e32 v64, 0xbfb8aa3b, v63
	v_exp_f32_e32 v64, v64
	s_nop 0
	v_add_f32_e32 v64, 1.0, v64
	v_rcp_f32_e32 v64, v64
	s_nop 0
	v_mul_f32_e32 v63, v63, v64
	v_cvt_pk_bf16_f32 v59, v62, v63
	ds_write2_b64 v110, v[60:61], v[58:59] offset0:132 offset1:198
	v_fmamk_f32 v58, v101, 0x3b800000, v189
	v_rsq_f32_e32 v58, v58
	s_nop 0
	v_pk_mul_f32 v[56:57], v[56:57], v[58:59] op_sel_hi:[1,0]
	s_nop 0
	v_pk_fma_f32 v[56:57], v[42:43], v[56:57], v[46:47]
	v_pk_mul_f32 v[58:59], v[72:73], v[58:59] op_sel_hi:[1,0]
	v_mul_f32_e32 v60, 0xbfb8aa3b, v56
	v_exp_f32_e32 v60, v60
	v_pk_fma_f32 v[58:59], v[44:45], v[58:59], v[48:49]
	v_add_f32_e32 v60, 1.0, v60
	v_rcp_f32_e32 v60, v60
	s_nop 0
	v_mul_f32_e32 v56, v56, v60
	v_mul_f32_e32 v60, 0xbfb8aa3b, v57
	v_exp_f32_e32 v60, v60
	s_nop 0
	v_add_f32_e32 v60, 1.0, v60
	v_rcp_f32_e32 v60, v60
	s_nop 0
	v_mul_f32_e32 v57, v57, v60
	v_mul_f32_e32 v60, 0xbfb8aa3b, v58
	v_exp_f32_e32 v60, v60
	v_cvt_pk_bf16_f32 v56, v56, v57
	s_nop 0
	v_add_f32_e32 v60, 1.0, v60
	v_rcp_f32_e32 v60, v60
	s_nop 0
	v_mul_f32_e32 v58, v58, v60
	v_mul_f32_e32 v60, 0xbfb8aa3b, v59
	v_exp_f32_e32 v60, v60
	s_nop 0
	v_add_f32_e32 v60, 1.0, v60
	v_rcp_f32_e32 v60, v60
	s_nop 0
	v_mul_f32_e32 v59, v59, v60
	v_cvt_pk_bf16_f32 v57, v58, v59
	v_fmamk_f32 v58, v102, 0x3b800000, v189
	v_rsq_f32_e32 v58, v58
	s_nop 0
	v_pk_mul_f32 v[54:55], v[54:55], v[58:59] op_sel_hi:[1,0]
	s_nop 0
	v_pk_fma_f32 v[54:55], v[42:43], v[54:55], v[46:47]
	v_pk_mul_f32 v[58:59], v[70:71], v[58:59] op_sel_hi:[1,0]
	v_mul_f32_e32 v60, 0xbfb8aa3b, v54
	v_exp_f32_e32 v60, v60
	v_pk_fma_f32 v[58:59], v[44:45], v[58:59], v[48:49]
	v_add_f32_e32 v60, 1.0, v60
	v_rcp_f32_e32 v60, v60
	s_nop 0
	v_mul_f32_e32 v54, v54, v60
	v_mul_f32_e32 v60, 0xbfb8aa3b, v55
	v_exp_f32_e32 v60, v60
	s_nop 0
	v_add_f32_e32 v60, 1.0, v60
	v_rcp_f32_e32 v60, v60
	s_nop 0
	v_mul_f32_e32 v55, v55, v60
	v_mul_f32_e32 v60, 0xbfb8aa3b, v58
	v_exp_f32_e32 v60, v60
	v_cvt_pk_bf16_f32 v54, v54, v55
	s_nop 0
	v_add_f32_e32 v60, 1.0, v60
	v_rcp_f32_e32 v60, v60
	s_nop 0
	v_mul_f32_e32 v58, v58, v60
	v_mul_f32_e32 v60, 0xbfb8aa3b, v59
	v_exp_f32_e32 v60, v60
	s_nop 0
	v_add_f32_e32 v60, 1.0, v60
	v_rcp_f32_e32 v60, v60
	s_nop 0
	v_mul_f32_e32 v59, v59, v60
	v_cvt_pk_bf16_f32 v55, v58, v59
	ds_write2_b64 v93, v[56:57], v[54:55] offset0:8 offset1:74
	v_fmamk_f32 v54, v103, 0x3b800000, v189
	v_rsq_f32_e32 v54, v54
	s_nop 0
	v_pk_mul_f32 v[52:53], v[52:53], v[54:55] op_sel_hi:[1,0]
	s_nop 0
	v_pk_fma_f32 v[52:53], v[42:43], v[52:53], v[46:47]
	v_pk_mul_f32 v[54:55], v[68:69], v[54:55] op_sel_hi:[1,0]
	v_mul_f32_e32 v56, 0xbfb8aa3b, v52
	v_exp_f32_e32 v56, v56
	v_pk_fma_f32 v[54:55], v[44:45], v[54:55], v[48:49]
	v_add_f32_e32 v56, 1.0, v56
	v_rcp_f32_e32 v56, v56
	s_nop 0
	v_mul_f32_e32 v52, v52, v56
	v_mul_f32_e32 v56, 0xbfb8aa3b, v53
	v_exp_f32_e32 v56, v56
	s_nop 0
	v_add_f32_e32 v56, 1.0, v56
	v_rcp_f32_e32 v56, v56
	s_nop 0
	v_mul_f32_e32 v53, v53, v56
	v_mul_f32_e32 v56, 0xbfb8aa3b, v54
	v_exp_f32_e32 v56, v56
	v_cvt_pk_bf16_f32 v52, v52, v53
	s_nop 0
	v_add_f32_e32 v56, 1.0, v56
	v_rcp_f32_e32 v56, v56
	s_nop 0
	v_mul_f32_e32 v54, v54, v56
	v_mul_f32_e32 v56, 0xbfb8aa3b, v55
	v_exp_f32_e32 v56, v56
	s_nop 0
	v_add_f32_e32 v56, 1.0, v56
	v_rcp_f32_e32 v56, v56
	s_nop 0
	v_mul_f32_e32 v55, v55, v56
	v_cvt_pk_bf16_f32 v53, v54, v55
	v_fmamk_f32 v54, v111, 0x3b800000, v189
	v_rsq_f32_e32 v54, v54
	s_nop 0
	v_pk_mul_f32 v[50:51], v[50:51], v[54:55] op_sel_hi:[1,0]
	s_nop 0
	v_pk_fma_f32 v[50:51], v[42:43], v[50:51], v[46:47]
	v_pk_mul_f32 v[54:55], v[66:67], v[54:55] op_sel_hi:[1,0]
	v_mul_f32_e32 v56, 0xbfb8aa3b, v50
	v_exp_f32_e32 v56, v56
	v_pk_fma_f32 v[54:55], v[44:45], v[54:55], v[48:49]
	v_add_f32_e32 v56, 1.0, v56
	v_rcp_f32_e32 v56, v56
	s_nop 0
	v_mul_f32_e32 v50, v50, v56
	v_mul_f32_e32 v56, 0xbfb8aa3b, v51
	v_exp_f32_e32 v56, v56
	s_nop 0
	v_add_f32_e32 v56, 1.0, v56
	v_rcp_f32_e32 v56, v56
	s_nop 0
	v_mul_f32_e32 v51, v51, v56
	v_mul_f32_e32 v56, 0xbfb8aa3b, v54
	v_exp_f32_e32 v56, v56
	v_cvt_pk_bf16_f32 v50, v50, v51
	s_nop 0
	v_add_f32_e32 v56, 1.0, v56
	v_rcp_f32_e32 v56, v56
	s_nop 0
	v_mul_f32_e32 v54, v54, v56
	v_mul_f32_e32 v56, 0xbfb8aa3b, v55
	v_exp_f32_e32 v56, v56
	s_nop 0
	v_add_f32_e32 v56, 1.0, v56
	v_rcp_f32_e32 v56, v56
	s_nop 0
	v_mul_f32_e32 v55, v55, v56
	v_cvt_pk_bf16_f32 v51, v54, v55
	ds_write2_b64 v93, v[52:53], v[50:51] offset0:140 offset1:206
	s_cbranch_vccz .LBB0_297
; #define LAS __attribute__((address_space(3)))
; __device__ __forceinline__ void mixer_chunk(KP p, LAS unsigned char* lds, int l, int chunk) {
;     ...
;     for (int i = 0; i < 6; ++i) { const int q = tid + 512 * i, r = q / 24, pc = q % 24; *(LAS u32x4*)(CQ + r * CQLD + 8 * pc) = sq[i]; }
; #pragma unroll
;     for (int i = 0; i < 4; ++i) { const int q = tid + 512 * i, r = q >> 4, pc = q & 15; *(LAS u32x4*)(CK + r * CKLD + 8 * pc) = sk[i]; }
;     __syncthreads();
;     f32x4 accc[8][2];
;     wgemm<8, 2>(accc, CO + fr * YLD + 8 * fq, YLD, (const bf16_t*)(ws + OFF_PW + l * SZ_PW) + (size_t)(32 * w + fr) * 256 + 8 * fq, 256);
;     ...
;         const int row = c0 + 16 * w + fr, spos = s0 + 16 * w + fr;
;         const bf16_t* zr = zb + (size_t)row * DIN_P; const float* rt = (const float*)(ws + OFF_ROPE) + (size_t)row * 32;
;         const u32x2 r1 = *(const u32x2*)(zr + ZC_KR + 4 * fq), r2 = *(const u32x2*)(zr + ZC_KR + 16 + 4 * fq);
;         const f32x4 cs = *(const f32x4*)(rt + 4 * fq), sn = *(const f32x4*)(rt + 16 + 4 * fq);
	s_movk_i32 s6, 0x190
	v_mul_lo_u32 v0, v74, s6
	v_lshlrev_b32_e32 v42, 4, v75
	v_add3_u32 v0, 0, v0, v42
	ds_write_b128 v0, v[2:5]
	v_mul_lo_u32 v0, v76, s6
	v_lshlrev_b32_e32 v2, 4, v77
	v_add3_u32 v0, 0, v0, v2
	ds_write_b128 v0, v[6:9]
	v_mul_lo_u32 v0, v78, s6
	v_lshlrev_b32_e32 v2, 4, v79
	v_add3_u32 v0, 0, v0, v2
	ds_write_b128 v0, v[10:13]
	v_mul_lo_u32 v0, v80, s6
	v_lshlrev_b32_e32 v2, 4, v81
	v_add3_u32 v0, 0, v0, v2
	ds_write_b128 v0, v[14:17]
	v_mul_lo_u32 v0, v82, s6
	v_lshlrev_b32_e32 v2, 4, v83
	v_add3_u32 v0, 0, v0, v2
	ds_write_b128 v0, v[18:21]
	v_mul_lo_u32 v0, v84, s6
	v_lshlrev_b32_e32 v2, 4, v85
	v_add3_u32 v0, 0, v0, v2
	ds_write_b128 v0, v[22:25]
	v_lshl_add_u32 v0, v87, 1, 0
	v_mad_u64_u32 v[2:3], s[6:7], v86, s64, v[0:1]
	ds_write_b128 v2, v[26:29] offset:51200
	v_mad_u64_u32 v[2:3], s[6:7], v88, s64, v[0:1]
	ds_write_b128 v2, v[30:33] offset:51200
	v_mad_u64_u32 v[2:3], s[6:7], v89, s64, v[0:1]
	v_and_b32_e32 v217, 15, v204
	ds_write_b128 v2, v[34:37] offset:51200
	v_mad_u64_u32 v[2:3], s[6:7], v90, s64, v[0:1]
	s_lshl_b32 s42, s55, 5
	ds_write_b128 v2, v[38:41] offset:51200
	v_or_b32_e32 v2, s42, v217
	v_ashrrev_i32_e32 v3, 31, v2
	v_readlane_b32 s6, v252, 8
	v_lshlrev_b64 v[2:3], 9, v[2:3]
	v_readlane_b32 s7, v252, 9
	v_and_b32_e32 v0, 48, v205
	s_waitcnt lgkmcnt(0)
	v_lshl_add_u64 v[2:3], s[6:7], 0, v[2:3]
	v_lshl_add_u64 v[6:7], v[2:3], 0, v[0:1]
	s_barrier
	global_load_dwordx4 v[118:121], v[6:7], off
	global_load_dwordx4 v[114:117], v[6:7], off offset:64
	global_load_dwordx4 v[110:113], v[6:7], off offset:128
	global_load_dwordx4 v[106:109], v[6:7], off offset:192
	global_load_dwordx4 v[102:105], v[6:7], off offset:256
	global_load_dwordx4 v[90:93], v[6:7], off offset:320
	global_load_dwordx4 v[86:89], v[6:7], off offset:384
	global_load_dwordx4 v[2:5], v[6:7], off offset:448
	v_add_co_u32_e32 v6, vcc, s39, v6
	v_mov_b32_e32 v10, s69
	s_nop 0
	v_addc_co_u32_e32 v7, vcc, 0, v7, vcc
	global_load_dwordx4 v[94:97], v[6:7], off
	global_load_dwordx4 v[98:101], v[6:7], off offset:64
	global_load_dwordx4 v[82:85], v[6:7], off offset:128
	global_load_dwordx4 v[78:81], v[6:7], off offset:192
	global_load_dwordx4 v[74:77], v[6:7], off offset:256
	global_load_dwordx4 v[70:73], v[6:7], off offset:320
	global_load_dwordx4 v[66:69], v[6:7], off offset:384
	s_nop 0
	global_load_dwordx4 v[6:9], v[6:7], off offset:448
	v_mov_b32_e32 v184, s88
	v_add_u32_e32 v184, s25, v184
	v_or_b32_e32 v184, v184, v217
	v_lshrrev_b32_e32 v186, 4, v205
	v_lshlrev_b32_e32 v185, 7, v184
	v_lshl_add_u32 v185, v186, 4, v185
	v_mul_u32_u24_e32 v184, s65, v184
	v_lshl_add_u32 v184, v186, 3, v184
	global_load_dwordx2 v[180:181], v184, s[44:45] offset:1664
	global_load_dwordx2 v[182:183], v184, s[44:45] offset:1696
	global_load_dwordx4 v[172:175], v185, s[92:93]
	global_load_dwordx4 v[176:179], v185, s[92:93] offset:64
	v_mad_u32_u24 v219, v217, s67, v10
	v_add_u32_e32 v0, v219, v0
	v_lshlrev_b32_e32 v220, 5, v217
	v_readlane_b32 s6, v254, 20
	s_movk_i32 s18, 0x190
	v_cmp_gt_u32_e64 s[40:41], 16, v205
	v_add_u32_e32 v215, s6, v220
	v_lshl_add_u32 v216, s55, 2, v215
	s_waitcnt vmcnt(12)
	s_waitcnt vmcnt(4)
	ds_read_b128 v[10:13], v0
	ds_read_b128 v[14:17], v0 offset:64
	ds_read_b128 v[22:25], v0 offset:8448
	ds_read_b128 v[26:29], v0 offset:8512
	s_waitcnt lgkmcnt(3)
	v_mfma_f32_16x16x32_bf16 v[18:21], v[118:121], v[10:13], 0
	v_mfma_f32_16x16x32_bf16 v[10:13], v[94:97], v[10:13], 0
	s_waitcnt lgkmcnt(1)
	v_mfma_f32_16x16x32_bf16 v[30:33], v[118:121], v[22:25], 0
	v_mfma_f32_16x16x32_bf16 v[22:25], v[94:97], v[22:25], 0
	v_mfma_f32_16x16x32_bf16 v[18:21], v[114:117], v[14:17], v[18:21]
	v_mfma_f32_16x16x32_bf16 v[10:13], v[98:101], v[14:17], v[10:13]
	s_waitcnt lgkmcnt(0)
	v_mfma_f32_16x16x32_bf16 v[14:17], v[114:117], v[26:29], v[30:33]
	v_mfma_f32_16x16x32_bf16 v[22:25], v[98:101], v[26:29], v[22:25]
	ds_read_b128 v[26:29], v0 offset:128
	s_nop 0
	ds_read_b128 v[30:33], v0 offset:192
	s_waitcnt lgkmcnt(1)
	v_mfma_f32_16x16x32_bf16 v[18:21], v[110:113], v[26:29], v[18:21]
	v_mfma_f32_16x16x32_bf16 v[10:13], v[82:85], v[26:29], v[10:13]
	ds_read_b128 v[26:29], v0 offset:8576
	ds_read_b128 v[34:37], v0 offset:8640
	s_waitcnt lgkmcnt(1)
	v_mfma_f32_16x16x32_bf16 v[14:17], v[110:113], v[26:29], v[14:17]
	v_mfma_f32_16x16x32_bf16 v[22:25], v[82:85], v[26:29], v[22:25]
	v_mfma_f32_16x16x32_bf16 v[18:21], v[106:109], v[30:33], v[18:21]
	v_mfma_f32_16x16x32_bf16 v[10:13], v[78:81], v[30:33], v[10:13]
	ds_read_b128 v[26:29], v0 offset:256
	ds_read_b128 v[30:33], v0 offset:320
	s_waitcnt lgkmcnt(2)
	v_mfma_f32_16x16x32_bf16 v[14:17], v[106:109], v[34:37], v[14:17]
	v_mfma_f32_16x16x32_bf16 v[22:25], v[78:81], v[34:37], v[22:25]
	s_waitcnt lgkmcnt(1)
	v_mfma_f32_16x16x32_bf16 v[18:21], v[102:105], v[26:29], v[18:21]
	v_mfma_f32_16x16x32_bf16 v[10:13], v[74:77], v[26:29], v[10:13]
	ds_read_b128 v[26:29], v0 offset:8704
	ds_read_b128 v[34:37], v0 offset:8768
	s_waitcnt lgkmcnt(1)
	v_mfma_f32_16x16x32_bf16 v[14:17], v[102:105], v[26:29], v[14:17]
	v_mfma_f32_16x16x32_bf16 v[22:25], v[74:77], v[26:29], v[22:25]
	v_mfma_f32_16x16x32_bf16 v[18:21], v[90:93], v[30:33], v[18:21]
	v_mfma_f32_16x16x32_bf16 v[10:13], v[70:73], v[30:33], v[10:13]
	ds_read_b128 v[26:29], v0 offset:384
	ds_read_b128 v[30:33], v0 offset:448
	s_waitcnt lgkmcnt(2)
	v_mfma_f32_16x16x32_bf16 v[14:17], v[90:93], v[34:37], v[14:17]
	s_waitcnt lgkmcnt(1)
	v_mfma_f32_16x16x32_bf16 v[18:21], v[86:89], v[26:29], v[18:21]
	v_mfma_f32_16x16x32_bf16 v[10:13], v[66:69], v[26:29], v[10:13]
	ds_read_b128 v[26:29], v0 offset:8832
	ds_read_b128 v[38:41], v0 offset:8896
	v_mfma_f32_16x16x32_bf16 v[22:25], v[70:73], v[34:37], v[22:25]
	s_waitcnt lgkmcnt(1)
; #define LAS __attribute__((address_space(3)))
; __device__ __forceinline__ f32x4 mfma16(bf16x8 a, bf16x8 b, f32x4 c) { return __builtin_amdgcn_mfma_f32_16x16x32_bf16(a, b, c, 0, 0, 0); }
; template <int NKS, int NNT>
; __device__ __forceinline__ void wgemm(f32x4 (&acc)[8][NNT], const LAS bf16_t* A, const int lda, const bf16_t* Bp, const int ldb) {
;     ...
; #pragma unroll
;     for (int mt = 0; mt < 8; ++mt) {
;         bf16x8 af[NKS];
; #pragma unroll
;         for (int ks = 0; ks < NKS; ++ks) af[ks] = *(const LAS bf16x8*)(A + (16 * mt) * lda + 32 * ks);
; #pragma unroll
;         for (int nt = 0; nt < NNT; ++nt) { f32x4 a = (f32x4){0.f, 0.f, 0.f, 0.f};
; #pragma unroll
;             for (int ks = 0; ks < NKS; ++ks) a = mfma16(as_bf16x8(bf[nt][ks]), af[ks], a);
;             acc[mt][nt] = a; }
;     }
	v_mfma_f32_16x16x32_bf16 v[14:17], v[86:89], v[26:29], v[14:17]
	v_mfma_f32_16x16x32_bf16 v[58:61], v[6:9], v[30:33], v[10:13]
	v_mfma_f32_16x16x32_bf16 v[10:13], v[66:69], v[26:29], v[22:25]
	s_waitcnt lgkmcnt(0)
	v_mfma_f32_16x16x32_bf16 v[54:57], v[2:5], v[38:41], v[14:17]
	v_mfma_f32_16x16x32_bf16 v[50:53], v[6:9], v[38:41], v[10:13]
	s_nop 4
	ds_read_b128 v[10:13], v0 offset:16896
	ds_read_b128 v[14:17], v0 offset:16960
	ds_read_b128 v[22:25], v0 offset:17024
	ds_read_b128 v[26:29], v0 offset:17088
	v_mfma_f32_16x16x32_bf16 v[62:65], v[2:5], v[30:33], v[18:21]
	ds_read_b128 v[30:33], v0 offset:17152
	ds_read_b128 v[34:37], v0 offset:17216
	ds_read_b128 v[38:41], v0 offset:17280
	ds_read_b128 v[42:45], v0 offset:17344
	s_waitcnt lgkmcnt(7)
	v_mfma_f32_16x16x32_bf16 v[18:21], v[118:121], v[10:13], 0
	v_mfma_f32_16x16x32_bf16 v[10:13], v[94:97], v[10:13], 0
	s_waitcnt lgkmcnt(6)
	v_mfma_f32_16x16x32_bf16 v[18:21], v[114:117], v[14:17], v[18:21]
	v_mfma_f32_16x16x32_bf16 v[10:13], v[98:101], v[14:17], v[10:13]
	s_waitcnt lgkmcnt(5)
	v_mfma_f32_16x16x32_bf16 v[18:21], v[110:113], v[22:25], v[18:21]
	v_mfma_f32_16x16x32_bf16 v[10:13], v[82:85], v[22:25], v[10:13]
	s_waitcnt lgkmcnt(4)
	v_mfma_f32_16x16x32_bf16 v[18:21], v[106:109], v[26:29], v[18:21]
	v_mfma_f32_16x16x32_bf16 v[10:13], v[78:81], v[26:29], v[10:13]
	s_waitcnt lgkmcnt(3)
	v_mfma_f32_16x16x32_bf16 v[18:21], v[102:105], v[30:33], v[18:21]
	v_mfma_f32_16x16x32_bf16 v[10:13], v[74:77], v[30:33], v[10:13]
	s_waitcnt lgkmcnt(2)
	v_mfma_f32_16x16x32_bf16 v[18:21], v[90:93], v[34:37], v[18:21]
	v_mfma_f32_16x16x32_bf16 v[10:13], v[70:73], v[34:37], v[10:13]
	s_waitcnt lgkmcnt(1)
	v_mfma_f32_16x16x32_bf16 v[18:21], v[86:89], v[38:41], v[18:21]
	v_mfma_f32_16x16x32_bf16 v[10:13], v[66:69], v[38:41], v[10:13]
	s_waitcnt lgkmcnt(0)
	v_mfma_f32_16x16x32_bf16 v[46:49], v[2:5], v[42:45], v[18:21]
	v_mfma_f32_16x16x32_bf16 v[42:45], v[6:9], v[42:45], v[10:13]
	s_nop 4
	ds_read_b128 v[10:13], v0 offset:25344
	ds_read_b128 v[14:17], v0 offset:25408
	ds_read_b128 v[22:25], v0 offset:25472
	ds_read_b128 v[26:29], v0 offset:25536
	ds_read_b128 v[30:33], v0 offset:25600
	ds_read_b128 v[34:37], v0 offset:25664
	s_waitcnt lgkmcnt(5)
	v_mfma_f32_16x16x32_bf16 v[18:21], v[118:121], v[10:13], 0
	ds_read_b128 v[122:125], v0 offset:25728
	ds_read_b128 v[126:129], v0 offset:25792
	v_mfma_f32_16x16x32_bf16 v[10:13], v[94:97], v[10:13], 0
	s_waitcnt lgkmcnt(6)
	v_mfma_f32_16x16x32_bf16 v[10:13], v[98:101], v[14:17], v[10:13]
	v_mfma_f32_16x16x32_bf16 v[18:21], v[114:117], v[14:17], v[18:21]
	s_waitcnt lgkmcnt(5)
	v_mfma_f32_16x16x32_bf16 v[10:13], v[82:85], v[22:25], v[10:13]
	v_mfma_f32_16x16x32_bf16 v[18:21], v[110:113], v[22:25], v[18:21]
	s_waitcnt lgkmcnt(4)
	v_mfma_f32_16x16x32_bf16 v[10:13], v[78:81], v[26:29], v[10:13]
	v_mfma_f32_16x16x32_bf16 v[18:21], v[106:109], v[26:29], v[18:21]
	s_waitcnt lgkmcnt(3)
	v_mfma_f32_16x16x32_bf16 v[10:13], v[74:77], v[30:33], v[10:13]
	v_mfma_f32_16x16x32_bf16 v[18:21], v[102:105], v[30:33], v[18:21]
	s_waitcnt lgkmcnt(2)
	v_mfma_f32_16x16x32_bf16 v[10:13], v[70:73], v[34:37], v[10:13]
	v_mfma_f32_16x16x32_bf16 v[18:21], v[90:93], v[34:37], v[18:21]
	s_waitcnt lgkmcnt(1)
	v_mfma_f32_16x16x32_bf16 v[10:13], v[66:69], v[122:125], v[10:13]
	v_mfma_f32_16x16x32_bf16 v[18:21], v[86:89], v[122:125], v[18:21]
	s_waitcnt lgkmcnt(0)
	v_mfma_f32_16x16x32_bf16 v[34:37], v[6:9], v[126:129], v[10:13]
	s_nop 4
	ds_read_b128 v[10:13], v0 offset:33792
	ds_read_b128 v[14:17], v0 offset:33856
	ds_read_b128 v[22:25], v0 offset:33920
	ds_read_b128 v[26:29], v0 offset:33984
	v_mfma_f32_16x16x32_bf16 v[38:41], v[2:5], v[126:129], v[18:21]
	ds_read_b128 v[122:125], v0 offset:34048
	ds_read_b128 v[126:129], v0 offset:34112
	ds_read_b128 v[130:133], v0 offset:34176
	ds_read_b128 v[134:137], v0 offset:34240
	s_waitcnt lgkmcnt(7)
	v_mfma_f32_16x16x32_bf16 v[18:21], v[118:121], v[10:13], 0
	v_mfma_f32_16x16x32_bf16 v[10:13], v[94:97], v[10:13], 0
	s_waitcnt lgkmcnt(6)
	v_mfma_f32_16x16x32_bf16 v[10:13], v[98:101], v[14:17], v[10:13]
	v_mfma_f32_16x16x32_bf16 v[18:21], v[114:117], v[14:17], v[18:21]
	s_waitcnt lgkmcnt(5)
	v_mfma_f32_16x16x32_bf16 v[10:13], v[82:85], v[22:25], v[10:13]
	v_mfma_f32_16x16x32_bf16 v[18:21], v[110:113], v[22:25], v[18:21]
	s_waitcnt lgkmcnt(4)
	v_mfma_f32_16x16x32_bf16 v[10:13], v[78:81], v[26:29], v[10:13]
	v_mfma_f32_16x16x32_bf16 v[18:21], v[106:109], v[26:29], v[18:21]
	s_waitcnt lgkmcnt(3)
	v_mfma_f32_16x16x32_bf16 v[10:13], v[74:77], v[122:125], v[10:13]
	v_mfma_f32_16x16x32_bf16 v[18:21], v[102:105], v[122:125], v[18:21]
	s_waitcnt lgkmcnt(2)
	v_mfma_f32_16x16x32_bf16 v[10:13], v[70:73], v[126:129], v[10:13]
	v_mfma_f32_16x16x32_bf16 v[18:21], v[90:93], v[126:129], v[18:21]
	s_waitcnt lgkmcnt(1)
	v_mfma_f32_16x16x32_bf16 v[10:13], v[66:69], v[130:133], v[10:13]
	v_mfma_f32_16x16x32_bf16 v[18:21], v[86:89], v[130:133], v[18:21]
	s_waitcnt lgkmcnt(0)
; #define LAS __attribute__((address_space(3)))
; __device__ __forceinline__ f32x4 mfma16(bf16x8 a, bf16x8 b, f32x4 c) { return __builtin_amdgcn_mfma_f32_16x16x32_bf16(a, b, c, 0, 0, 0); }
; template <int NKS, int NNT>
; __device__ __forceinline__ void wgemm(f32x4 (&acc)[8][NNT], const LAS bf16_t* A, const int lda, const bf16_t* Bp, const int ldb) {
;     ...
; #pragma unroll
;     for (int mt = 0; mt < 8; ++mt) {
;         bf16x8 af[NKS];
; #pragma unroll
;         for (int ks = 0; ks < NKS; ++ks) af[ks] = *(const LAS bf16x8*)(A + (16 * mt) * lda + 32 * ks);
; #pragma unroll
;         for (int nt = 0; nt < NNT; ++nt) { f32x4 a = (f32x4){0.f, 0.f, 0.f, 0.f};
; #pragma unroll
;             for (int ks = 0; ks < NKS; ++ks) a = mfma16(as_bf16x8(bf[nt][ks]), af[ks], a);
;             acc[mt][nt] = a; }
;     }
; }
; template <int NNT>
; __device__ __forceinline__ void part_sumsq(const f32x4 (&acc)[8][NNT], LAS float* part, int w, int fr, int fq) {
; #pragma unroll
;     for (int mt = 0; mt < 8; ++mt) { float s = 0.f;
; #pragma unroll
;         for (int nt = 0; nt < NNT; ++nt) s += (acc[mt][nt][0] * acc[mt][nt][0] + acc[mt][nt][1] * acc[mt][nt][1]) + (acc[mt][nt][2] * acc[mt][nt][2] + acc[mt][nt][3] * acc[mt][nt][3]);
;         s += __shfl_xor(s, 16); s += __shfl_xor(s, 32);
;         if (fq == 0) part[(16 * mt + fr) * 8 + w] = s; }
	v_mfma_f32_16x16x32_bf16 v[26:29], v[6:9], v[134:137], v[10:13]
	s_nop 4
	ds_read_b128 v[10:13], v0 offset:42240
	ds_read_b128 v[14:17], v0 offset:42304
	ds_read_b128 v[122:125], v0 offset:42368
	ds_read_b128 v[126:129], v0 offset:42432
	v_mfma_f32_16x16x32_bf16 v[30:33], v[2:5], v[134:137], v[18:21]
	ds_read_b128 v[130:133], v0 offset:42496
	ds_read_b128 v[134:137], v0 offset:42560
	ds_read_b128 v[138:141], v0 offset:42624
	ds_read_b128 v[142:145], v0 offset:42688
	s_waitcnt lgkmcnt(7)
	v_mfma_f32_16x16x32_bf16 v[18:21], v[118:121], v[10:13], 0
	v_mfma_f32_16x16x32_bf16 v[10:13], v[94:97], v[10:13], 0
	s_waitcnt lgkmcnt(6)
	v_mfma_f32_16x16x32_bf16 v[18:21], v[114:117], v[14:17], v[18:21]
	v_mfma_f32_16x16x32_bf16 v[10:13], v[98:101], v[14:17], v[10:13]
	s_waitcnt lgkmcnt(5)
	v_mfma_f32_16x16x32_bf16 v[18:21], v[110:113], v[122:125], v[18:21]
	v_mfma_f32_16x16x32_bf16 v[10:13], v[82:85], v[122:125], v[10:13]
	s_waitcnt lgkmcnt(4)
	v_mfma_f32_16x16x32_bf16 v[18:21], v[106:109], v[126:129], v[18:21]
	v_mfma_f32_16x16x32_bf16 v[10:13], v[78:81], v[126:129], v[10:13]
	s_waitcnt lgkmcnt(3)
	v_mfma_f32_16x16x32_bf16 v[18:21], v[102:105], v[130:133], v[18:21]
	v_mfma_f32_16x16x32_bf16 v[10:13], v[74:77], v[130:133], v[10:13]
	s_waitcnt lgkmcnt(2)
	v_mfma_f32_16x16x32_bf16 v[18:21], v[90:93], v[134:137], v[18:21]
	v_mfma_f32_16x16x32_bf16 v[10:13], v[70:73], v[134:137], v[10:13]
	s_waitcnt lgkmcnt(1)
	v_mfma_f32_16x16x32_bf16 v[18:21], v[86:89], v[138:141], v[18:21]
	v_mfma_f32_16x16x32_bf16 v[10:13], v[66:69], v[138:141], v[10:13]
	s_waitcnt lgkmcnt(0)
	v_mfma_f32_16x16x32_bf16 v[22:25], v[2:5], v[142:145], v[18:21]
	v_mfma_f32_16x16x32_bf16 v[18:21], v[6:9], v[142:145], v[10:13]
	s_nop 4
	ds_read_b128 v[10:13], v0 offset:50688
	ds_read_b128 v[122:125], v0 offset:50752
	ds_read_b128 v[126:129], v0 offset:50816
	ds_read_b128 v[130:133], v0 offset:50880
	ds_read_b128 v[134:137], v0 offset:50944
	ds_read_b128 v[138:141], v0 offset:51008
	s_waitcnt lgkmcnt(5)
	v_mfma_f32_16x16x32_bf16 v[14:17], v[118:121], v[10:13], 0
	ds_read_b128 v[142:145], v0 offset:51072
	ds_read_b128 v[146:149], v0 offset:51136
	v_mfma_f32_16x16x32_bf16 v[10:13], v[94:97], v[10:13], 0
	s_waitcnt lgkmcnt(6)
	v_mfma_f32_16x16x32_bf16 v[14:17], v[114:117], v[122:125], v[14:17]
	v_mfma_f32_16x16x32_bf16 v[10:13], v[98:101], v[122:125], v[10:13]
	s_waitcnt lgkmcnt(5)
	v_mfma_f32_16x16x32_bf16 v[14:17], v[110:113], v[126:129], v[14:17]
	v_mfma_f32_16x16x32_bf16 v[10:13], v[82:85], v[126:129], v[10:13]
	ds_read_b128 v[122:125], v0 offset:59136
	ds_read_b128 v[126:129], v0 offset:59200
	s_waitcnt lgkmcnt(1)
	v_mfma_f32_16x16x32_bf16 v[118:121], v[118:121], v[122:125], 0
	v_mfma_f32_16x16x32_bf16 v[14:17], v[106:109], v[130:133], v[14:17]
	v_mfma_f32_16x16x32_bf16 v[10:13], v[78:81], v[130:133], v[10:13]
	s_waitcnt lgkmcnt(0)
	v_mfma_f32_16x16x32_bf16 v[114:117], v[114:117], v[126:129], v[118:121]
	s_nop 3
	ds_read_b128 v[118:121], v0 offset:59264
	ds_read_b128 v[130:133], v0 offset:59328
	s_waitcnt lgkmcnt(1)
	v_mfma_f32_16x16x32_bf16 v[110:113], v[110:113], v[118:121], v[114:117]
	s_waitcnt lgkmcnt(0)
	v_mfma_f32_16x16x32_bf16 v[106:109], v[106:109], v[130:133], v[110:113]
	s_nop 5
	ds_read_b128 v[110:113], v0 offset:59392
	ds_read_b128 v[114:117], v0 offset:59456
	v_mfma_f32_16x16x32_bf16 v[14:17], v[102:105], v[134:137], v[14:17]
	s_waitcnt lgkmcnt(1)
	v_mfma_f32_16x16x32_bf16 v[102:105], v[102:105], v[110:113], v[106:109]
	v_mfma_f32_16x16x32_bf16 v[14:17], v[90:93], v[138:141], v[14:17]
	s_waitcnt lgkmcnt(0)
	v_mfma_f32_16x16x32_bf16 v[90:93], v[90:93], v[114:117], v[102:105]
	s_nop 4
	ds_read_b128 v[102:105], v0 offset:59520
	ds_read_b128 v[106:109], v0 offset:59584
	v_mul_f32_e32 v0, v63, v63
	v_fmac_f32_e32 v0, v62, v62
	v_mfma_f32_16x16x32_bf16 v[14:17], v[86:89], v[142:145], v[14:17]
	s_waitcnt lgkmcnt(1)
	v_mfma_f32_16x16x32_bf16 v[86:89], v[86:89], v[102:105], v[90:93]
	v_mfma_f32_16x16x32_bf16 v[14:17], v[2:5], v[146:149], v[14:17]
	s_waitcnt lgkmcnt(0)
	v_mfma_f32_16x16x32_bf16 v[2:5], v[2:5], v[106:109], v[86:89]
	v_mfma_f32_16x16x32_bf16 v[86:89], v[94:97], v[122:125], 0
	v_mfma_f32_16x16x32_bf16 v[86:89], v[98:101], v[126:129], v[86:89]
	v_mfma_f32_16x16x32_bf16 v[82:85], v[82:85], v[118:121], v[86:89]
	v_mfma_f32_16x16x32_bf16 v[78:81], v[78:81], v[130:133], v[82:85]
	s_nop 5
	v_mul_f32_e32 v86, v65, v65
	v_fmac_f32_e32 v86, v64, v64
	v_add_f32_e32 v0, v0, v86
	v_mfma_f32_16x16x32_bf16 v[10:13], v[74:77], v[134:137], v[10:13]
	v_mul_f32_e32 v82, v59, v59
	v_fmac_f32_e32 v82, v58, v58
	v_mfma_f32_16x16x32_bf16 v[74:77], v[74:77], v[110:113], v[78:81]
	s_nop 2
	v_mul_f32_e32 v78, v61, v61
	v_fmac_f32_e32 v78, v60, v60
	v_add_f32_e32 v78, v82, v78
	v_mfma_f32_16x16x32_bf16 v[10:13], v[70:73], v[138:141], v[10:13]
	v_add_f32_e32 v0, v0, v78
	v_mfma_f32_16x16x32_bf16 v[70:73], v[70:73], v[114:117], v[74:77]
	s_nop 2
	ds_bpermute_b32 v74, v207, v0
	v_mfma_f32_16x16x32_bf16 v[10:13], v[66:69], v[142:145], v[10:13]
	s_waitcnt lgkmcnt(0)
	v_add_f32_e32 v0, v0, v74
	v_mfma_f32_16x16x32_bf16 v[68:71], v[66:69], v[102:105], v[70:73]
	ds_bpermute_b32 v66, v208, v0
	v_mfma_f32_16x16x32_bf16 v[10:13], v[6:9], v[146:149], v[10:13]
	v_mfma_f32_16x16x32_bf16 v[6:9], v[6:9], v[106:109], v[68:71]
	s_and_saveexec_b64 s[6:7], s[40:41]
	s_cbranch_execz .LBB0_300
	s_waitcnt lgkmcnt(0)
	v_add_f32_e32 v0, v0, v66
	ds_write_b32 v216, v0

; __device__ __forceinline__ unsigned pk2(float lo, float hi) { unsigned r; asm("v_cvt_pk_bf16_f32 %0, %1, %2" : "=v"(r) : "v"(lo), "v"(hi)); return r; }
; __device__ __forceinline__ float bf_lo(unsigned w) { return __uint_as_float(w << 16); }
; __device__ __forceinline__ float bf_hi(unsigned w) { return __uint_as_float(w & 0xffff0000u); }
; __device__ __forceinline__ void mixer_chunk(KP p, LAS unsigned char* lds, int l, int chunk) {
;     ...
;         const int row = c0 + 16 * w + fr, spos = s0 + 16 * w + fr;
;         const bf16_t* zr = zb + (size_t)row * DIN_P; const float* rt = (const float*)(ws + OFF_ROPE) + (size_t)row * 32;
;         const u32x2 r1 = *(const u32x2*)(zr + ZC_KR + 4 * fq), r2 = *(const u32x2*)(zr + ZC_KR + 16 + 4 * fq);
;         const f32x4 cs = *(const f32x4*)(rt + 4 * fq), sn = *(const f32x4*)(rt + 16 + 4 * fq);
;         const f32x4 k1 = (f32x4){bf_lo(r1.x), bf_hi(r1.x), bf_lo(r1.y), bf_hi(r1.y)}, k2 = (f32x4){bf_lo(r2.x), bf_hi(r2.x), bf_lo(r2.y), bf_hi(r2.y)};
;         const f32x4 o1 = k1 * cs - k2 * sn, o2 = k2 * cs + k1 * sn;
;         u32x2 ro1, ro2; ro1.x = pk2(o1[0], o1[1]); ro1.y = pk2(o1[2], o1[3]); ro2.x = pk2(o2[0], o2[1]); ro2.y = pk2(o2[2], o2[3]);
;         bf16_t* kd = (bf16_t*)(ws + OFF_K) + ((size_t)(bidx * 4) * SEQ + spos) * 96 + 64 + 4 * fq;
; #pragma unroll
;         for (int h = 0; h < 4; ++h) { *(u32x2*)(kd + (size_t)h * SEQ * 96) = ro1; *(u32x2*)(kd + (size_t)h * SEQ * 96 + 16) = ro2; }
;     }
;     __syncthreads();
.LBB0_316:
	s_or_b64 exec, exec, s[6:7]
	v_or_b32_e32 v168, s25, v217
	v_ashrrev_i32_e32 v169, 31, v168
	v_readlane_b32 s6, v252, 6
	v_lshlrev_b64 v[70:71], 11, v[168:169]
	v_readlane_b32 s7, v252, 7
	v_mov_b32_e32 v67, v1
	s_add_i32 s89, s88, s25
	v_lshl_add_u64 v[70:71], s[6:7], 0, v[70:71]
	v_lshl_add_u64 v[170:171], v[70:71], 0, v[66:67]
	v_or_b32_e32 v70, s89, v217
	s_add_i32 s6, s88, s24
	v_ashrrev_i32_e32 v71, 31, v70
	s_waitcnt lgkmcnt(0)
	v_mov_b64_e32 v[72:73], s[44:45]
	v_or_b32_e32 v76, s6, v217
	v_mad_i64_i32 v[72:73], s[6:7], v70, s65, v[72:73]
	v_lshlrev_b64 v[70:71], 7, v[70:71]
	v_lshlrev_b32_e32 v221, 2, v68
	v_lshl_add_u64 v[70:71], s[92:93], 0, v[70:71]
	v_lshl_add_u64 v[72:73], v[72:73], 0, v[66:67]
	v_lshlrev_b32_e32 v68, 4, v68
	v_mov_b32_e32 v69, v1
	s_waitcnt vmcnt(0)
	v_mov_b64_e32 v[78:79], v[180:181]
	v_mov_b64_e32 v[80:81], v[182:183]
	v_lshl_add_u64 v[72:73], v[70:71], 0, v[68:69]
	v_mov_b64_e32 v[68:69], v[172:173]
	v_mov_b64_e32 v[70:71], v[174:175]
	s_nop 0
	v_mov_b64_e32 v[72:73], v[176:177]
	v_mov_b64_e32 v[74:75], v[178:179]
	s_nop 0
	s_ashr_i32 s6, s23, 3
	s_and_b32 s96, s6, -4
	s_ashr_i32 s97, s96, 31
	s_lshl_b64 s[6:7], s[96:97], 12
	v_ashrrev_i32_e32 v77, 31, v76
	s_ashr_i32 s43, s42, 31
	s_cmp_eq_u32 s46, 0
	s_waitcnt vmcnt(3)
	v_lshlrev_b32_e32 v82, 16, v78
	s_waitcnt vmcnt(2)
	v_lshlrev_b32_e32 v84, 16, v80
	v_and_b32_e32 v85, 0xffff0000, v80
	v_lshlrev_b32_e32 v80, 16, v81
	v_and_b32_e32 v81, 0xffff0000, v81
	v_and_b32_e32 v83, 0xffff0000, v78
	v_lshlrev_b32_e32 v78, 16, v79
	v_and_b32_e32 v79, 0xffff0000, v79
	s_waitcnt vmcnt(0)
	v_pk_mul_f32 v[86:87], v[74:75], v[80:81]
	v_pk_mul_f32 v[88:89], v[72:73], v[84:85]
	v_pk_fma_f32 v[86:87], v[70:71], v[78:79], v[86:87] neg_lo:[0,0,1] neg_hi:[0,0,1]
	v_pk_fma_f32 v[88:89], v[68:69], v[82:83], v[88:89] neg_lo:[0,0,1] neg_hi:[0,0,1]
	v_pk_mul_f32 v[70:71], v[70:71], v[80:81]
	v_pk_mul_f32 v[68:69], v[68:69], v[84:85]
	v_pk_fma_f32 v[70:71], v[74:75], v[78:79], v[70:71]
	v_pk_fma_f32 v[68:69], v[72:73], v[82:83], v[68:69]
	v_mov_b64_e32 v[74:75], s[12:13]
	v_cvt_pk_bf16_f32 v68, v68, v69
	v_cvt_pk_bf16_f32 v69, v70, v71
	v_lshl_add_u64 v[70:71], s[6:7], 0, v[76:77]
	v_mad_u64_u32 v[74:75], s[6:7], v70, s57, v[74:75]
	v_mad_i32_i24 v75, v71, s57, v75
	v_lshl_add_u64 v[66:67], v[74:75], 0, v[66:67]
	s_mov_b32 s6, 0xc0000
	v_add_co_u32_e32 v70, vcc, s6, v66
	v_cvt_pk_bf16_f32 v72, v88, v89
	v_cvt_pk_bf16_f32 v73, v86, v87
	s_mov_b32 s6, 0x180000
	s_nop 0
	v_addc_co_u32_e32 v71, vcc, 0, v67, vcc
	s_nop 1
	v_mov_b32_e32 v244, v72
	v_mov_b32_e32 v245, v73
	v_mov_b32_e32 v246, v68
	v_mov_b32_e32 v247, v69
	v_bfe_u32 v248, v193, 4, 1
	v_mul_u32_u24_e32 v248, 24, v248
	v_add_co_u32_e64 v248, s[98:99], v248, v66
	s_nop 1
	v_addc_co_u32_e64 v249, s[98:99], 0, v67, s[98:99]
	v_permlane16_swap_b32_e32 v244, v246
	v_permlane16_swap_b32_e32 v245, v247
	global_store_dwordx4 v[248:249], v[244:247], off offset:128
	s_nop 1
	v_mov_b32_e32 v244, v72
	v_mov_b32_e32 v245, v73
	v_mov_b32_e32 v246, v68
	v_mov_b32_e32 v247, v69
	v_bfe_u32 v248, v193, 4, 1
	v_mul_u32_u24_e32 v248, 24, v248
	v_add_co_u32_e64 v248, s[98:99], v248, v70
	s_nop 1
	v_addc_co_u32_e64 v249, s[98:99], 0, v71, s[98:99]
	v_permlane16_swap_b32_e32 v244, v246
	v_permlane16_swap_b32_e32 v245, v247
	global_store_dwordx4 v[248:249], v[244:247], off offset:128
	v_add_co_u32_e32 v70, vcc, s6, v66
	s_mov_b32 s6, 0x240000
	s_nop 0
	v_addc_co_u32_e32 v71, vcc, 0, v67, vcc
	v_add_co_u32_e32 v66, vcc, s6, v66
	s_nop 1
	v_mov_b32_e32 v244, v72
	v_mov_b32_e32 v245, v73
	v_mov_b32_e32 v246, v68
	v_mov_b32_e32 v247, v69
	v_bfe_u32 v248, v193, 4, 1
	v_mul_u32_u24_e32 v248, 24, v248
	v_add_co_u32_e64 v248, s[98:99], v248, v70
	s_nop 1
	v_addc_co_u32_e64 v249, s[98:99], 0, v71, s[98:99]
	v_permlane16_swap_b32_e32 v244, v246
	v_permlane16_swap_b32_e32 v245, v247
	global_store_dwordx4 v[248:249], v[244:247], off offset:128
	v_addc_co_u32_e32 v67, vcc, 0, v67, vcc
	s_nop 1
	v_mov_b32_e32 v244, v72
	v_mov_b32_e32 v245, v73
	v_mov_b32_e32 v246, v68
	v_mov_b32_e32 v247, v69
	v_bfe_u32 v248, v193, 4, 1
	v_mul_u32_u24_e32 v248, 24, v248
	v_add_co_u32_e64 v248, s[98:99], v248, v66
	s_nop 1
	v_addc_co_u32_e64 v249, s[98:99], 0, v67, s[98:99]
	v_permlane16_swap_b32_e32 v244, v246
	v_permlane16_swap_b32_e32 v245, v247
	global_store_dwordx4 v[248:249], v[244:247], off offset:128
	s_barrier
; #define LAS __attribute__((address_space(3)))
; __device__ __forceinline__ unsigned pk2(float lo, float hi) { unsigned r; asm("v_cvt_pk_bf16_f32 %0, %1, %2" : "=v"(r) : "v"(lo), "v"(hi)); return r; }
; __device__ __forceinline__ float rsq(float x) { return __builtin_amdgcn_rsqf(x); }
; template <int NKS, int NNT>
; __device__ __forceinline__ void wgemm(f32x4 (&acc)[8][NNT], const LAS bf16_t* A, const int lda, const bf16_t* Bp, const int ldb) {
;     ...
;     for (int nt = 0; nt < NNT; ++nt) ldfr(bf[nt], Bp + (size_t)(16 * nt) * ldb);
; template <int NNT>
; __device__ __forceinline__ void norm_store(const f32x4 (&acc)[8][NNT], const LAS float* part, bf16_t* dst, int fr) {
; #pragma unroll
;     for (int mt = 0; mt < 8; ++mt) {
;         const LAS f32x4* pp = (const LAS f32x4*)(part + (16 * mt + fr) * 8); const f32x4 a = pp[0], b = pp[1];
;         const float rs = rsq((((a[0] + a[1]) + (a[2] + a[3])) + ((b[0] + b[1]) + (b[2] + b[3]))) * (1.0f / 256.0f) + EPS);
; #pragma unroll
;         for (int nt = 0; nt < NNT; ++nt) { u32x2 o; o.x = pk2(acc[mt][nt][0] * rs, acc[mt][nt][1] * rs); o.y = pk2(acc[mt][nt][2] * rs, acc[mt][nt][3] * rs);
;             *(u32x2*)(dst + (size_t)(16 * mt) * DM + 16 * nt) = o; }
;     }
; __device__ __forceinline__ void mixer_chunk(KP p, LAS unsigned char* lds, int l, int chunk) {
;     ...
;     norm_store<2>(accc, part0, mrow + 0 + 32 * w, fr);
	s_mul_i32 s100, s55, 48
	v_or_b32_e32 v158, s100, v217
	v_mul_u32_u24_e32 v158, 0x180, v158
	v_and_b32_e32 v159, 48, v205
	v_add_u32_e32 v158, v158, v159
	v_add_u32_e32 v159, 0x1800, v158
	v_add_u32_e32 v160, 0x3000, v158
	global_load_dwordx4 v[154:157], v158, s[10:11]
	global_load_dwordx4 v[150:153], v158, s[10:11] offset:64
	global_load_dwordx4 v[142:145], v158, s[10:11] offset:128
	global_load_dwordx4 v[138:141], v158, s[10:11] offset:192
	global_load_dwordx4 v[172:175], v158, s[10:11] offset:256
	global_load_dwordx4 v[176:179], v158, s[10:11] offset:320
	global_load_dwordx4 v[180:183], v159, s[10:11]
	global_load_dwordx4 v[98:101], v159, s[10:11] offset:64
	global_load_dwordx4 v[102:105], v159, s[10:11] offset:128
	global_load_dwordx4 v[106:109], v159, s[10:11] offset:192
	global_load_dwordx4 v[110:113], v159, s[10:11] offset:256
	global_load_dwordx4 v[114:117], v159, s[10:11] offset:320
	global_load_dwordx4 v[146:149], v160, s[10:11]
	global_load_dwordx4 v[118:121], v160, s[10:11] offset:64
	global_load_dwordx4 v[122:125], v160, s[10:11] offset:128
	global_load_dwordx4 v[126:129], v160, s[10:11] offset:192
	global_load_dwordx4 v[130:133], v160, s[10:11] offset:256
	global_load_dwordx4 v[134:137], v160, s[10:11] offset:320
	ds_read_b128 v[68:71], v215
	ds_read_b128 v[72:75], v215 offset:16
	v_lshl_add_u64 v[66:67], s[42:43], 1, v[170:171]
	s_mov_b32 s6, 0x8000
	s_cselect_b64 s[42:43], -1, 0
	s_waitcnt lgkmcnt(1)
	v_mov_b32_e32 v76, v68
	s_waitcnt lgkmcnt(0)
	v_mov_b32_e32 v77, v72
	v_mov_b32_e32 v72, v69
	v_pk_add_f32 v[68:69], v[76:77], v[72:73]
	v_mov_b32_e32 v72, v70
	v_mov_b32_e32 v73, v74
	v_mov_b32_e32 v74, v71
	v_pk_add_f32 v[70:71], v[72:73], v[74:75]
	s_cmp_lg_u32 s46, 0
	v_pk_add_f32 v[68:69], v[68:69], v[70:71]
	s_cselect_b64 s[90:91], -1, 0
	v_add_f32_e32 v68, v68, v69
	v_fmamk_f32 v68, v68, 0x3b800000, v189
	v_rsq_f32_e32 v68, v68
	s_nop 0
	v_mul_f32_e32 v62, v62, v68
	v_mul_f32_e32 v63, v63, v68
	v_mul_f32_e32 v58, v58, v68
	v_mul_f32_e32 v59, v59, v68
	v_cvt_pk_bf16_f32 v62, v62, v63
	v_mul_f32_e32 v63, v64, v68
	v_cvt_pk_bf16_f32 v58, v58, v59
	v_mul_f32_e32 v59, v60, v68
	v_mul_f32_e32 v64, v65, v68
	v_cvt_pk_bf16_f32 v63, v63, v64
	s_nop 1
	v_mov_b32_e32 v244, v62
	v_mov_b32_e32 v245, v63
	v_mul_f32_e32 v60, v61, v68
	v_cvt_pk_bf16_f32 v59, v59, v60
	v_mov_b32_e32 v246, v58
	v_mov_b32_e32 v247, v59
	v_bfe_u32 v248, v193, 4, 1
	v_mul_u32_u24_e32 v248, 24, v248
	v_add_co_u32_e64 v248, s[98:99], v248, v66
	s_nop 1
	v_addc_co_u32_e64 v249, s[98:99], 0, v67, s[98:99]
	v_permlane16_swap_b32_e32 v244, v246
	v_permlane16_swap_b32_e32 v245, v247
	global_store_dwordx4 v[248:249], v[244:247], off
	ds_read_b128 v[58:61], v215 offset:512
	ds_read_b128 v[62:65], v215 offset:528
	s_waitcnt lgkmcnt(1)
	v_mov_b32_e32 v68, v58
	s_waitcnt lgkmcnt(0)
	v_mov_b32_e32 v69, v62
	v_mov_b32_e32 v62, v59
	v_pk_add_f32 v[58:59], v[68:69], v[62:63]
	v_mov_b32_e32 v62, v60
	v_mov_b32_e32 v63, v64
	v_mov_b32_e32 v64, v61
	v_pk_add_f32 v[60:61], v[62:63], v[64:65]
	s_nop 0
	v_pk_add_f32 v[58:59], v[58:59], v[60:61]
	s_nop 0
	v_add_f32_e32 v58, v58, v59
	v_fmamk_f32 v58, v58, 0x3b800000, v189
	v_rsq_f32_e32 v58, v58
	s_nop 0
	v_mul_f32_e32 v54, v54, v58
	v_mul_f32_e32 v55, v55, v58
	v_cvt_pk_bf16_f32 v54, v54, v55
	v_mul_f32_e32 v55, v56, v58
	v_mul_f32_e32 v56, v57, v58
	v_cvt_pk_bf16_f32 v55, v55, v56
	v_add_co_u32_e32 v56, vcc, s6, v66
	v_mul_f32_e32 v50, v50, v58
	v_mul_f32_e32 v51, v51, v58
	v_addc_co_u32_e32 v57, vcc, 0, v67, vcc
	v_cvt_pk_bf16_f32 v50, v50, v51
	v_mul_f32_e32 v51, v52, v58
	s_nop 1
	v_mov_b32_e32 v244, v54
	v_mov_b32_e32 v245, v55
	v_mul_f32_e32 v52, v53, v58
	v_cvt_pk_bf16_f32 v51, v51, v52
	v_mov_b32_e32 v246, v50
	v_mov_b32_e32 v247, v51
	v_bfe_u32 v248, v193, 4, 1
	v_mul_u32_u24_e32 v248, 24, v248
	v_add_co_u32_e64 v248, s[98:99], v248, v56
	s_nop 1
	v_addc_co_u32_e64 v249, s[98:99], 0, v57, s[98:99]
	v_permlane16_swap_b32_e32 v244, v246
	v_permlane16_swap_b32_e32 v245, v247
	global_store_dwordx4 v[248:249], v[244:247], off
	ds_read_b128 v[50:53], v215 offset:1024
	ds_read_b128 v[54:57], v215 offset:1040
	s_mov_b32 s6, 0x18000
	s_waitcnt lgkmcnt(1)
	v_mov_b32_e32 v58, v50
	s_waitcnt lgkmcnt(0)
	v_mov_b32_e32 v59, v54
	v_mov_b32_e32 v54, v51
	v_pk_add_f32 v[50:51], v[58:59], v[54:55]
	v_mov_b32_e32 v54, v52
	v_mov_b32_e32 v55, v56
	v_mov_b32_e32 v56, v53
	v_pk_add_f32 v[52:53], v[54:55], v[56:57]
	s_nop 0
	v_pk_add_f32 v[50:51], v[50:51], v[52:53]
	s_nop 0
	v_add_f32_e32 v50, v50, v51
	v_fmamk_f32 v50, v50, 0x3b800000, v189
	v_rsq_f32_e32 v50, v50
	s_nop 0
	v_mul_f32_e32 v46, v46, v50
	v_mul_f32_e32 v47, v47, v50
	v_cvt_pk_bf16_f32 v46, v46, v47
	v_mul_f32_e32 v47, v48, v50
	v_mul_f32_e32 v48, v49, v50
	v_cvt_pk_bf16_f32 v47, v47, v48
	v_add_co_u32_e32 v48, vcc, s72, v66
	v_mul_f32_e32 v42, v42, v50
	v_mul_f32_e32 v43, v43, v50
	v_addc_co_u32_e32 v49, vcc, 0, v67, vcc
	v_cvt_pk_bf16_f32 v42, v42, v43
	v_mul_f32_e32 v43, v44, v50
	s_nop 1
	v_mov_b32_e32 v244, v46
	v_mov_b32_e32 v245, v47
	v_mul_f32_e32 v44, v45, v50
	v_cvt_pk_bf16_f32 v43, v43, v44
	v_mov_b32_e32 v246, v42
	v_mov_b32_e32 v247, v43
	v_bfe_u32 v248, v193, 4, 1
	v_mul_u32_u24_e32 v248, 24, v248
	v_add_co_u32_e64 v248, s[98:99], v248, v48
	s_nop 1
	v_addc_co_u32_e64 v249, s[98:99], 0, v49, s[98:99]
	v_permlane16_swap_b32_e32 v244, v246
	v_permlane16_swap_b32_e32 v245, v247
	global_store_dwordx4 v[248:249], v[244:247], off
	ds_read_b128 v[42:45], v215 offset:1536
	ds_read_b128 v[46:49], v215 offset:1552
	s_waitcnt lgkmcnt(1)
	v_mov_b32_e32 v50, v42
	s_waitcnt lgkmcnt(0)
; #define LAS __attribute__((address_space(3)))
; __device__ __forceinline__ unsigned pk2(float lo, float hi) { unsigned r; asm("v_cvt_pk_bf16_f32 %0, %1, %2" : "=v"(r) : "v"(lo), "v"(hi)); return r; }
; __device__ __forceinline__ float rsq(float x) { return __builtin_amdgcn_rsqf(x); }
; template <int NNT>
; __device__ __forceinline__ void norm_store(const f32x4 (&acc)[8][NNT], const LAS float* part, bf16_t* dst, int fr) {
; #pragma unroll
;     for (int mt = 0; mt < 8; ++mt) {
;         const LAS f32x4* pp = (const LAS f32x4*)(part + (16 * mt + fr) * 8); const f32x4 a = pp[0], b = pp[1];
;         const float rs = rsq((((a[0] + a[1]) + (a[2] + a[3])) + ((b[0] + b[1]) + (b[2] + b[3]))) * (1.0f / 256.0f) + EPS);
; #pragma unroll
;         for (int nt = 0; nt < NNT; ++nt) { u32x2 o; o.x = pk2(acc[mt][nt][0] * rs, acc[mt][nt][1] * rs); o.y = pk2(acc[mt][nt][2] * rs, acc[mt][nt][3] * rs);
;             *(u32x2*)(dst + (size_t)(16 * mt) * DM + 16 * nt) = o; }
;     }
	v_mov_b32_e32 v51, v46
	v_mov_b32_e32 v46, v43
	v_pk_add_f32 v[42:43], v[50:51], v[46:47]
	v_mov_b32_e32 v46, v44
	v_mov_b32_e32 v47, v48
	v_mov_b32_e32 v48, v45
	v_pk_add_f32 v[44:45], v[46:47], v[48:49]
	s_nop 0
	v_pk_add_f32 v[42:43], v[42:43], v[44:45]
	s_nop 0
	v_add_f32_e32 v42, v42, v43
	v_fmamk_f32 v42, v42, 0x3b800000, v189
	v_rsq_f32_e32 v42, v42
	s_nop 0
	v_mul_f32_e32 v38, v38, v42
	v_mul_f32_e32 v39, v39, v42
	v_cvt_pk_bf16_f32 v38, v38, v39
	v_mul_f32_e32 v39, v40, v42
	v_mul_f32_e32 v40, v41, v42
	v_cvt_pk_bf16_f32 v39, v39, v40
	v_add_co_u32_e32 v40, vcc, s6, v66
	v_mul_f32_e32 v34, v34, v42
	v_mul_f32_e32 v35, v35, v42
	v_addc_co_u32_e32 v41, vcc, 0, v67, vcc
	v_cvt_pk_bf16_f32 v34, v34, v35
	v_mul_f32_e32 v35, v36, v42
	s_nop 1
	v_mov_b32_e32 v244, v38
	v_mov_b32_e32 v245, v39
	v_mul_f32_e32 v36, v37, v42
	v_cvt_pk_bf16_f32 v35, v35, v36
	v_mov_b32_e32 v246, v34
	v_mov_b32_e32 v247, v35
	v_bfe_u32 v248, v193, 4, 1
	v_mul_u32_u24_e32 v248, 24, v248
	v_add_co_u32_e64 v248, s[98:99], v248, v40
	s_nop 1
	v_addc_co_u32_e64 v249, s[98:99], 0, v41, s[98:99]
	v_permlane16_swap_b32_e32 v244, v246
	v_permlane16_swap_b32_e32 v245, v247
	global_store_dwordx4 v[248:249], v[244:247], off
	ds_read_b128 v[34:37], v215 offset:2048
	ds_read_b128 v[38:41], v215 offset:2064
	s_mov_b32 s6, 0x20000
	s_waitcnt lgkmcnt(1)
	v_mov_b32_e32 v42, v34
	s_waitcnt lgkmcnt(0)
	v_mov_b32_e32 v43, v38
	v_mov_b32_e32 v38, v35
	v_pk_add_f32 v[34:35], v[42:43], v[38:39]
	v_mov_b32_e32 v38, v36
	v_mov_b32_e32 v39, v40
	v_mov_b32_e32 v40, v37
	v_pk_add_f32 v[36:37], v[38:39], v[40:41]
	s_nop 0
	v_pk_add_f32 v[34:35], v[34:35], v[36:37]
	s_nop 0
	v_add_f32_e32 v34, v34, v35
	v_fmamk_f32 v34, v34, 0x3b800000, v189
	v_rsq_f32_e32 v34, v34
	s_nop 0
	v_mul_f32_e32 v30, v30, v34
	v_mul_f32_e32 v31, v31, v34
	v_cvt_pk_bf16_f32 v30, v30, v31
	v_mul_f32_e32 v31, v32, v34
	v_mul_f32_e32 v32, v33, v34
	v_cvt_pk_bf16_f32 v31, v31, v32
	v_add_co_u32_e32 v32, vcc, s6, v66
	v_mul_f32_e32 v26, v26, v34
	v_mul_f32_e32 v27, v27, v34
	v_addc_co_u32_e32 v33, vcc, 0, v67, vcc
	v_cvt_pk_bf16_f32 v26, v26, v27
	v_mul_f32_e32 v27, v28, v34
	s_nop 1
	v_mov_b32_e32 v244, v30
	v_mov_b32_e32 v245, v31
	v_mul_f32_e32 v28, v29, v34
	v_cvt_pk_bf16_f32 v27, v27, v28
	v_mov_b32_e32 v246, v26
	v_mov_b32_e32 v247, v27
	v_bfe_u32 v248, v193, 4, 1
	v_mul_u32_u24_e32 v248, 24, v248
	v_add_co_u32_e64 v248, s[98:99], v248, v32
	s_nop 1
	v_addc_co_u32_e64 v249, s[98:99], 0, v33, s[98:99]
	v_permlane16_swap_b32_e32 v244, v246
	v_permlane16_swap_b32_e32 v245, v247
	global_store_dwordx4 v[248:249], v[244:247], off
	ds_read_b128 v[26:29], v215 offset:2560
	ds_read_b128 v[30:33], v215 offset:2576
	s_mov_b32 s6, 0x28000
	s_waitcnt lgkmcnt(1)
	v_mov_b32_e32 v34, v26
	s_waitcnt lgkmcnt(0)
	v_mov_b32_e32 v35, v30
	v_mov_b32_e32 v30, v27
	v_pk_add_f32 v[26:27], v[34:35], v[30:31]
	v_mov_b32_e32 v30, v28
	v_mov_b32_e32 v31, v32
	v_mov_b32_e32 v32, v29
	v_pk_add_f32 v[28:29], v[30:31], v[32:33]
	s_nop 0
	v_pk_add_f32 v[26:27], v[26:27], v[28:29]
	s_nop 0
	v_add_f32_e32 v26, v26, v27
	v_fmamk_f32 v26, v26, 0x3b800000, v189
	v_rsq_f32_e32 v26, v26
	s_nop 0
	v_mul_f32_e32 v22, v22, v26
	v_mul_f32_e32 v23, v23, v26
	v_cvt_pk_bf16_f32 v22, v22, v23
	v_mul_f32_e32 v23, v24, v26
	v_mul_f32_e32 v24, v25, v26
	v_cvt_pk_bf16_f32 v23, v23, v24
	v_add_co_u32_e32 v24, vcc, s6, v66
	v_mul_f32_e32 v18, v18, v26
	v_mul_f32_e32 v19, v19, v26
	v_addc_co_u32_e32 v25, vcc, 0, v67, vcc
	v_cvt_pk_bf16_f32 v18, v18, v19
	v_mul_f32_e32 v19, v20, v26
	s_nop 1
	v_mov_b32_e32 v244, v22
	v_mov_b32_e32 v245, v23
	v_mul_f32_e32 v20, v21, v26
	v_cvt_pk_bf16_f32 v19, v19, v20
	v_mov_b32_e32 v246, v18
	v_mov_b32_e32 v247, v19
	v_bfe_u32 v248, v193, 4, 1
	v_mul_u32_u24_e32 v248, 24, v248
	v_add_co_u32_e64 v248, s[98:99], v248, v24
	s_nop 1
	v_addc_co_u32_e64 v249, s[98:99], 0, v25, s[98:99]
	v_permlane16_swap_b32_e32 v244, v246
	v_permlane16_swap_b32_e32 v245, v247
	global_store_dwordx4 v[248:249], v[244:247], off
	ds_read_b128 v[18:21], v215 offset:3072
	ds_read_b128 v[22:25], v215 offset:3088
	s_mov_b32 s6, 0x30000
	s_waitcnt lgkmcnt(1)
	v_mov_b32_e32 v26, v18
	s_waitcnt lgkmcnt(0)
	v_mov_b32_e32 v27, v22
	v_mov_b32_e32 v22, v19
	v_pk_add_f32 v[18:19], v[26:27], v[22:23]
	v_mov_b32_e32 v22, v20
	v_mov_b32_e32 v23, v24
	v_mov_b32_e32 v24, v21
	v_pk_add_f32 v[20:21], v[22:23], v[24:25]
	s_nop 0
	v_pk_add_f32 v[18:19], v[18:19], v[20:21]
	s_nop 0
	v_add_f32_e32 v18, v18, v19
	v_fmamk_f32 v18, v18, 0x3b800000, v189
	v_rsq_f32_e32 v18, v18
	s_nop 0
	v_mul_f32_e32 v14, v14, v18
	v_mul_f32_e32 v15, v15, v18
	v_cvt_pk_bf16_f32 v14, v14, v15
	v_mul_f32_e32 v15, v16, v18
	v_mul_f32_e32 v16, v17, v18
	v_cvt_pk_bf16_f32 v15, v15, v16
	v_add_co_u32_e32 v16, vcc, s6, v66
	v_mul_f32_e32 v10, v10, v18
	v_mul_f32_e32 v11, v11, v18
	v_addc_co_u32_e32 v17, vcc, 0, v67, vcc
	v_cvt_pk_bf16_f32 v10, v10, v11
	v_mul_f32_e32 v11, v12, v18
	s_nop 1
	v_mov_b32_e32 v244, v14
	v_mov_b32_e32 v245, v15
	v_mul_f32_e32 v12, v13, v18
	v_cvt_pk_bf16_f32 v11, v11, v12
	v_mov_b32_e32 v246, v10
	v_mov_b32_e32 v247, v11
	v_bfe_u32 v248, v193, 4, 1
	v_mul_u32_u24_e32 v248, 24, v248
	v_add_co_u32_e64 v248, s[98:99], v248, v16
	s_nop 1
	v_addc_co_u32_e64 v249, s[98:99], 0, v17, s[98:99]
	v_permlane16_swap_b32_e32 v244, v246
	v_permlane16_swap_b32_e32 v245, v247
	global_store_dwordx4 v[248:249], v[244:247], off
	ds_read_b128 v[10:13], v215 offset:3584
	ds_read_b128 v[14:17], v215 offset:3600
	s_mov_b32 s6, 0x38000
	s_waitcnt lgkmcnt(1)
	v_mov_b32_e32 v18, v10
	s_waitcnt lgkmcnt(0)
; #define LAS __attribute__((address_space(3)))
; __device__ __forceinline__ unsigned pk2(float lo, float hi) { unsigned r; asm("v_cvt_pk_bf16_f32 %0, %1, %2" : "=v"(r) : "v"(lo), "v"(hi)); return r; }
; __device__ __forceinline__ f32x4 mfma16(bf16x8 a, bf16x8 b, f32x4 c) { return __builtin_amdgcn_mfma_f32_16x16x32_bf16(a, b, c, 0, 0, 0); }
; __device__ __forceinline__ float rsq(float x) { return __builtin_amdgcn_rsqf(x); }
; template <int NKS, int NNT>
; __device__ __forceinline__ void wgemm(f32x4 (&acc)[8][NNT], const LAS bf16_t* A, const int lda, const bf16_t* Bp, const int ldb) {
;     ...
; #pragma unroll
;     for (int mt = 0; mt < 8; ++mt) {
;         bf16x8 af[NKS];
; #pragma unroll
;         for (int ks = 0; ks < NKS; ++ks) af[ks] = *(const LAS bf16x8*)(A + (16 * mt) * lda + 32 * ks);
; #pragma unroll
;         for (int nt = 0; nt < NNT; ++nt) { f32x4 a = (f32x4){0.f, 0.f, 0.f, 0.f};
; #pragma unroll
;             for (int ks = 0; ks < NKS; ++ks) a = mfma16(as_bf16x8(bf[nt][ks]), af[ks], a);
;             acc[mt][nt] = a; }
;     }
; template <int NNT>
; __device__ __forceinline__ void norm_store(const f32x4 (&acc)[8][NNT], const LAS float* part, bf16_t* dst, int fr) {
;     ...
;     for (int mt = 0; mt < 8; ++mt) {
;         const LAS f32x4* pp = (const LAS f32x4*)(part + (16 * mt + fr) * 8); const f32x4 a = pp[0], b = pp[1];
;         const float rs = rsq((((a[0] + a[1]) + (a[2] + a[3])) + ((b[0] + b[1]) + (b[2] + b[3]))) * (1.0f / 256.0f) + EPS);
; #pragma unroll
;         for (int nt = 0; nt < NNT; ++nt) { u32x2 o; o.x = pk2(acc[mt][nt][0] * rs, acc[mt][nt][1] * rs); o.y = pk2(acc[mt][nt][2] * rs, acc[mt][nt][3] * rs);
;             *(u32x2*)(dst + (size_t)(16 * mt) * DM + 16 * nt) = o; }
;     }
; __device__ __forceinline__ void mixer_chunk(KP p, LAS unsigned char* lds, int l, int chunk) {
;     ...
;         wgemm<6, 3>(acc, CQ + fr * CQLD + 8 * fq, CQLD, (const bf16_t*)(ws + OFF_UQ + l * SZ_UQ) + (size_t)(48 * w + fr) * 192 + 8 * fq, 192);
	v_mov_b32_e32 v19, v14
	v_mov_b32_e32 v14, v11
	v_pk_add_f32 v[10:11], v[18:19], v[14:15]
	v_mov_b32_e32 v14, v12
	v_mov_b32_e32 v15, v16
	v_mov_b32_e32 v16, v13
	v_pk_add_f32 v[12:13], v[14:15], v[16:17]
	s_nop 0
	v_pk_add_f32 v[10:11], v[10:11], v[12:13]
	s_nop 0
	v_add_f32_e32 v10, v10, v11
	v_fmamk_f32 v10, v10, 0x3b800000, v189
	v_rsq_f32_e32 v10, v10
	s_nop 0
	v_mul_f32_e32 v2, v2, v10
	v_mul_f32_e32 v3, v3, v10
	v_cvt_pk_bf16_f32 v2, v2, v3
	v_mul_f32_e32 v3, v4, v10
	v_mul_f32_e32 v4, v5, v10
	v_cvt_pk_bf16_f32 v3, v3, v4
	v_add_co_u32_e32 v4, vcc, s6, v66
	s_mul_i32 s6, s55, 48
	s_nop 0
	v_addc_co_u32_e32 v5, vcc, 0, v67, vcc
	s_nop 1
	v_mov_b32_e32 v244, v2
	v_mov_b32_e32 v245, v3
	v_mul_f32_e32 v2, v6, v10
	v_mul_f32_e32 v3, v7, v10
	v_cvt_pk_bf16_f32 v2, v2, v3
	v_mul_f32_e32 v3, v8, v10
	v_mul_f32_e32 v6, v9, v10
	v_cvt_pk_bf16_f32 v3, v3, v6
	v_mov_b32_e32 v246, v2
	v_mov_b32_e32 v247, v3
	v_bfe_u32 v248, v193, 4, 1
	v_mul_u32_u24_e32 v248, 24, v248
	v_add_co_u32_e64 v248, s[98:99], v248, v4
	s_nop 1
	v_addc_co_u32_e64 v249, s[98:99], 0, v5, s[98:99]
	v_permlane16_swap_b32_e32 v244, v246
	v_permlane16_swap_b32_e32 v245, v247
	global_store_dwordx4 v[248:249], v[244:247], off
	v_mul_u32_u24_e32 v2, 0x190, v217
	v_add3_u32 v162, 0, v2, v0
	v_or_b32_e32 v4, s6, v217
	v_mov_b64_e32 v[2:3], s[10:11]
	s_movk_i32 s6, 0x180
	v_mad_i64_i32 v[2:3], s[6:7], v4, s6, v[2:3]
	v_lshl_add_u64 v[10:11], v[2:3], 0, v[0:1]
	s_movk_i32 s6, 0x1000
	v_add_co_u32_e32 v12, vcc, s6, v10
	v_addc_co_u32_e32 v13, vcc, 0, v11, vcc
	v_add_co_u32_e32 v10, vcc, s68, v10
	v_addc_co_u32_e32 v11, vcc, 0, v11, vcc
	s_waitcnt vmcnt(8)
	v_mov_b64_e32 v[6:7], v[172:173]
	v_mov_b64_e32 v[8:9], v[174:175]
	v_mov_b64_e32 v[2:3], v[176:177]
	v_mov_b64_e32 v[4:5], v[178:179]
	v_mov_b64_e32 v[22:23], v[180:181]
	v_mov_b64_e32 v[24:25], v[182:183]
	s_waitcnt vmcnt(8)
	s_waitcnt vmcnt(8)
	ds_read_b128 v[10:13], v162
	ds_read_b128 v[14:17], v162 offset:64
	ds_read_b128 v[18:21], v162 offset:128
	ds_read_b128 v[26:29], v162 offset:192
	ds_read_b128 v[30:33], v162 offset:256
	ds_read_b128 v[34:37], v162 offset:320
	s_waitcnt lgkmcnt(5)
	v_mfma_f32_16x16x32_bf16 v[38:41], v[154:157], v[10:13], 0
	s_and_b64 vcc, exec, s[42:43]
	s_waitcnt lgkmcnt(4)
	v_mfma_f32_16x16x32_bf16 v[38:41], v[150:153], v[14:17], v[38:41]
	s_waitcnt lgkmcnt(3)
	v_mfma_f32_16x16x32_bf16 v[38:41], v[142:145], v[18:21], v[38:41]
	s_waitcnt lgkmcnt(2)
	v_mfma_f32_16x16x32_bf16 v[38:41], v[138:141], v[26:29], v[38:41]
	s_waitcnt lgkmcnt(1)
	v_mfma_f32_16x16x32_bf16 v[38:41], v[6:9], v[30:33], v[38:41]
	s_waitcnt lgkmcnt(0)
	v_mfma_f32_16x16x32_bf16 v[82:85], v[2:5], v[34:37], v[38:41]
	v_mfma_f32_16x16x32_bf16 v[38:41], v[22:25], v[10:13], 0
	v_mfma_f32_16x16x32_bf16 v[10:13], v[146:149], v[10:13], 0
	v_mfma_f32_16x16x32_bf16 v[38:41], v[98:101], v[14:17], v[38:41]
	v_mfma_f32_16x16x32_bf16 v[10:13], v[118:121], v[14:17], v[10:13]
	v_mfma_f32_16x16x32_bf16 v[38:41], v[102:105], v[18:21], v[38:41]
	v_mfma_f32_16x16x32_bf16 v[10:13], v[122:125], v[18:21], v[10:13]
	v_mfma_f32_16x16x32_bf16 v[38:41], v[106:109], v[26:29], v[38:41]
	v_mfma_f32_16x16x32_bf16 v[10:13], v[126:129], v[26:29], v[10:13]
	v_mfma_f32_16x16x32_bf16 v[38:41], v[110:113], v[30:33], v[38:41]
	v_mfma_f32_16x16x32_bf16 v[10:13], v[130:133], v[30:33], v[10:13]
	v_mfma_f32_16x16x32_bf16 v[90:93], v[114:117], v[34:37], v[38:41]
	v_mfma_f32_16x16x32_bf16 v[94:97], v[134:137], v[34:37], v[10:13]
	s_nop 5
	ds_read_b128 v[10:13], v162 offset:6400
	ds_read_b128 v[14:17], v162 offset:6464
	ds_read_b128 v[18:21], v162 offset:6528
	ds_read_b128 v[26:29], v162 offset:6592
	ds_read_b128 v[30:33], v162 offset:6656
	ds_read_b128 v[34:37], v162 offset:6720
	s_waitcnt lgkmcnt(5)
	v_mfma_f32_16x16x32_bf16 v[38:41], v[154:157], v[10:13], 0
	s_waitcnt lgkmcnt(4)
	v_mfma_f32_16x16x32_bf16 v[38:41], v[150:153], v[14:17], v[38:41]
	s_waitcnt lgkmcnt(3)
	v_mfma_f32_16x16x32_bf16 v[38:41], v[142:145], v[18:21], v[38:41]
	s_waitcnt lgkmcnt(2)
	v_mfma_f32_16x16x32_bf16 v[38:41], v[138:141], v[26:29], v[38:41]
	s_waitcnt lgkmcnt(1)
	v_mfma_f32_16x16x32_bf16 v[38:41], v[6:9], v[30:33], v[38:41]
	s_waitcnt lgkmcnt(0)
	v_mfma_f32_16x16x32_bf16 v[74:77], v[2:5], v[34:37], v[38:41]
	v_mfma_f32_16x16x32_bf16 v[38:41], v[22:25], v[10:13], 0
	v_mfma_f32_16x16x32_bf16 v[10:13], v[146:149], v[10:13], 0
	v_mfma_f32_16x16x32_bf16 v[38:41], v[98:101], v[14:17], v[38:41]
	v_mfma_f32_16x16x32_bf16 v[10:13], v[118:121], v[14:17], v[10:13]
	v_mfma_f32_16x16x32_bf16 v[38:41], v[102:105], v[18:21], v[38:41]
	v_mfma_f32_16x16x32_bf16 v[10:13], v[122:125], v[18:21], v[10:13]
	v_mfma_f32_16x16x32_bf16 v[38:41], v[106:109], v[26:29], v[38:41]
	v_mfma_f32_16x16x32_bf16 v[10:13], v[126:129], v[26:29], v[10:13]
	v_mfma_f32_16x16x32_bf16 v[38:41], v[110:113], v[30:33], v[38:41]
	v_mfma_f32_16x16x32_bf16 v[10:13], v[130:133], v[30:33], v[10:13]
	v_mfma_f32_16x16x32_bf16 v[78:81], v[114:117], v[34:37], v[38:41]
	v_mfma_f32_16x16x32_bf16 v[86:89], v[134:137], v[34:37], v[10:13]
	s_nop 5
	ds_read_b128 v[10:13], v162 offset:12800
	ds_read_b128 v[14:17], v162 offset:12864
	ds_read_b128 v[18:21], v162 offset:12928
	ds_read_b128 v[26:29], v162 offset:12992
	ds_read_b128 v[30:33], v162 offset:13056
	ds_read_b128 v[34:37], v162 offset:13120
	s_waitcnt lgkmcnt(5)
	v_mfma_f32_16x16x32_bf16 v[38:41], v[154:157], v[10:13], 0
	s_waitcnt lgkmcnt(4)
	v_mfma_f32_16x16x32_bf16 v[38:41], v[150:153], v[14:17], v[38:41]
	s_waitcnt lgkmcnt(3)
	v_mfma_f32_16x16x32_bf16 v[38:41], v[142:145], v[18:21], v[38:41]
	s_waitcnt lgkmcnt(2)
	v_mfma_f32_16x16x32_bf16 v[38:41], v[138:141], v[26:29], v[38:41]
	s_waitcnt lgkmcnt(1)
; #define LAS __attribute__((address_space(3)))
; __device__ __forceinline__ f32x4 mfma16(bf16x8 a, bf16x8 b, f32x4 c) { return __builtin_amdgcn_mfma_f32_16x16x32_bf16(a, b, c, 0, 0, 0); }
; template <int NKS, int NNT>
; __device__ __forceinline__ void wgemm(f32x4 (&acc)[8][NNT], const LAS bf16_t* A, const int lda, const bf16_t* Bp, const int ldb) {
;     ...
; #pragma unroll
;     for (int mt = 0; mt < 8; ++mt) {
;         bf16x8 af[NKS];
; #pragma unroll
;         for (int ks = 0; ks < NKS; ++ks) af[ks] = *(const LAS bf16x8*)(A + (16 * mt) * lda + 32 * ks);
; #pragma unroll
;         for (int nt = 0; nt < NNT; ++nt) { f32x4 a = (f32x4){0.f, 0.f, 0.f, 0.f};
; #pragma unroll
;             for (int ks = 0; ks < NKS; ++ks) a = mfma16(as_bf16x8(bf[nt][ks]), af[ks], a);
;             acc[mt][nt] = a; }
;     }
	v_mfma_f32_16x16x32_bf16 v[38:41], v[6:9], v[30:33], v[38:41]
	s_waitcnt lgkmcnt(0)
	v_mfma_f32_16x16x32_bf16 v[62:65], v[2:5], v[34:37], v[38:41]
	v_mfma_f32_16x16x32_bf16 v[38:41], v[22:25], v[10:13], 0
	v_mfma_f32_16x16x32_bf16 v[10:13], v[146:149], v[10:13], 0
	v_mfma_f32_16x16x32_bf16 v[38:41], v[98:101], v[14:17], v[38:41]
	v_mfma_f32_16x16x32_bf16 v[10:13], v[118:121], v[14:17], v[10:13]
	v_mfma_f32_16x16x32_bf16 v[38:41], v[102:105], v[18:21], v[38:41]
	v_mfma_f32_16x16x32_bf16 v[10:13], v[122:125], v[18:21], v[10:13]
	v_mfma_f32_16x16x32_bf16 v[38:41], v[106:109], v[26:29], v[38:41]
	v_mfma_f32_16x16x32_bf16 v[10:13], v[126:129], v[26:29], v[10:13]
	v_mfma_f32_16x16x32_bf16 v[38:41], v[110:113], v[30:33], v[38:41]
	v_mfma_f32_16x16x32_bf16 v[10:13], v[130:133], v[30:33], v[10:13]
	v_mfma_f32_16x16x32_bf16 v[66:69], v[114:117], v[34:37], v[38:41]
	v_mfma_f32_16x16x32_bf16 v[70:73], v[134:137], v[34:37], v[10:13]
	s_nop 5
	ds_read_b128 v[10:13], v162 offset:19200
	ds_read_b128 v[14:17], v162 offset:19264
	ds_read_b128 v[18:21], v162 offset:19328
	ds_read_b128 v[26:29], v162 offset:19392
	ds_read_b128 v[30:33], v162 offset:19456
	ds_read_b128 v[34:37], v162 offset:19520
	s_waitcnt lgkmcnt(5)
	v_mfma_f32_16x16x32_bf16 v[38:41], v[154:157], v[10:13], 0
	s_waitcnt lgkmcnt(4)
	v_mfma_f32_16x16x32_bf16 v[38:41], v[150:153], v[14:17], v[38:41]
	s_waitcnt lgkmcnt(3)
	v_mfma_f32_16x16x32_bf16 v[38:41], v[142:145], v[18:21], v[38:41]
	s_waitcnt lgkmcnt(2)
	v_mfma_f32_16x16x32_bf16 v[38:41], v[138:141], v[26:29], v[38:41]
	s_waitcnt lgkmcnt(1)
	v_mfma_f32_16x16x32_bf16 v[38:41], v[6:9], v[30:33], v[38:41]
	s_waitcnt lgkmcnt(0)
	v_mfma_f32_16x16x32_bf16 v[50:53], v[2:5], v[34:37], v[38:41]
	v_mfma_f32_16x16x32_bf16 v[38:41], v[22:25], v[10:13], 0
	v_mfma_f32_16x16x32_bf16 v[10:13], v[146:149], v[10:13], 0
	v_mfma_f32_16x16x32_bf16 v[38:41], v[98:101], v[14:17], v[38:41]
	v_mfma_f32_16x16x32_bf16 v[10:13], v[118:121], v[14:17], v[10:13]
	v_mfma_f32_16x16x32_bf16 v[38:41], v[102:105], v[18:21], v[38:41]
	v_mfma_f32_16x16x32_bf16 v[10:13], v[122:125], v[18:21], v[10:13]
	v_mfma_f32_16x16x32_bf16 v[38:41], v[106:109], v[26:29], v[38:41]
	v_mfma_f32_16x16x32_bf16 v[10:13], v[126:129], v[26:29], v[10:13]
	v_mfma_f32_16x16x32_bf16 v[38:41], v[110:113], v[30:33], v[38:41]
	v_mfma_f32_16x16x32_bf16 v[10:13], v[130:133], v[30:33], v[10:13]
	v_mfma_f32_16x16x32_bf16 v[54:57], v[114:117], v[34:37], v[38:41]
	v_mfma_f32_16x16x32_bf16 v[58:61], v[134:137], v[34:37], v[10:13]
	s_nop 5
	ds_read_b128 v[10:13], v162 offset:25600
	ds_read_b128 v[14:17], v162 offset:25664
	ds_read_b128 v[18:21], v162 offset:25728
	ds_read_b128 v[26:29], v162 offset:25792
	ds_read_b128 v[34:37], v162 offset:25856
	ds_read_b128 v[42:45], v162 offset:25920
	s_waitcnt lgkmcnt(5)
	v_mfma_f32_16x16x32_bf16 v[30:33], v[154:157], v[10:13], 0
	v_mfma_f32_16x16x32_bf16 v[38:41], v[22:25], v[10:13], 0
	v_mfma_f32_16x16x32_bf16 v[10:13], v[146:149], v[10:13], 0
	s_waitcnt lgkmcnt(4)
	v_mfma_f32_16x16x32_bf16 v[30:33], v[150:153], v[14:17], v[30:33]
	v_mfma_f32_16x16x32_bf16 v[38:41], v[98:101], v[14:17], v[38:41]
	v_mfma_f32_16x16x32_bf16 v[10:13], v[118:121], v[14:17], v[10:13]
	s_waitcnt lgkmcnt(3)
	v_mfma_f32_16x16x32_bf16 v[30:33], v[142:145], v[18:21], v[30:33]
	v_mfma_f32_16x16x32_bf16 v[38:41], v[102:105], v[18:21], v[38:41]
	v_mfma_f32_16x16x32_bf16 v[10:13], v[122:125], v[18:21], v[10:13]
	s_waitcnt lgkmcnt(2)
	v_mfma_f32_16x16x32_bf16 v[30:33], v[138:141], v[26:29], v[30:33]
	v_mfma_f32_16x16x32_bf16 v[38:41], v[106:109], v[26:29], v[38:41]
	v_mfma_f32_16x16x32_bf16 v[10:13], v[126:129], v[26:29], v[10:13]
	s_waitcnt lgkmcnt(1)
	v_mfma_f32_16x16x32_bf16 v[30:33], v[6:9], v[34:37], v[30:33]
	v_mfma_f32_16x16x32_bf16 v[38:41], v[110:113], v[34:37], v[38:41]
	v_mfma_f32_16x16x32_bf16 v[10:13], v[130:133], v[34:37], v[10:13]
	s_waitcnt lgkmcnt(0)
	v_mfma_f32_16x16x32_bf16 v[30:33], v[2:5], v[42:45], v[30:33]
	v_mfma_f32_16x16x32_bf16 v[38:41], v[114:117], v[42:45], v[38:41]
	v_mfma_f32_16x16x32_bf16 v[46:49], v[134:137], v[42:45], v[10:13]
	s_nop 3
	ds_read_b128 v[10:13], v162 offset:32000
	ds_read_b128 v[14:17], v162 offset:32064
	ds_read_b128 v[18:21], v162 offset:32128
	ds_read_b128 v[42:45], v162 offset:32192
	ds_read_b128 v[158:161], v162 offset:32256
	ds_read_b128 v[172:175], v162 offset:32320
	s_waitcnt lgkmcnt(5)
	v_mfma_f32_16x16x32_bf16 v[26:29], v[154:157], v[10:13], 0
	v_mfma_f32_16x16x32_bf16 v[34:37], v[22:25], v[10:13], 0
	v_mfma_f32_16x16x32_bf16 v[10:13], v[146:149], v[10:13], 0
	s_waitcnt lgkmcnt(4)
	v_mfma_f32_16x16x32_bf16 v[26:29], v[150:153], v[14:17], v[26:29]
	v_mfma_f32_16x16x32_bf16 v[34:37], v[98:101], v[14:17], v[34:37]
	v_mfma_f32_16x16x32_bf16 v[10:13], v[118:121], v[14:17], v[10:13]
	s_waitcnt lgkmcnt(3)
	v_mfma_f32_16x16x32_bf16 v[26:29], v[142:145], v[18:21], v[26:29]
	v_mfma_f32_16x16x32_bf16 v[34:37], v[102:105], v[18:21], v[34:37]
	v_mfma_f32_16x16x32_bf16 v[10:13], v[122:125], v[18:21], v[10:13]
	s_waitcnt lgkmcnt(2)
	v_mfma_f32_16x16x32_bf16 v[26:29], v[138:141], v[42:45], v[26:29]
	v_mfma_f32_16x16x32_bf16 v[34:37], v[106:109], v[42:45], v[34:37]
	v_mfma_f32_16x16x32_bf16 v[10:13], v[126:129], v[42:45], v[10:13]
	s_waitcnt lgkmcnt(1)
	v_mfma_f32_16x16x32_bf16 v[26:29], v[6:9], v[158:161], v[26:29]
	v_mfma_f32_16x16x32_bf16 v[34:37], v[110:113], v[158:161], v[34:37]
	v_mfma_f32_16x16x32_bf16 v[10:13], v[130:133], v[158:161], v[10:13]
	s_waitcnt lgkmcnt(0)
; #define LAS __attribute__((address_space(3)))
; __device__ __forceinline__ f32x4 mfma16(bf16x8 a, bf16x8 b, f32x4 c) { return __builtin_amdgcn_mfma_f32_16x16x32_bf16(a, b, c, 0, 0, 0); }
; template <int NKS, int NNT>
; __device__ __forceinline__ void wgemm(f32x4 (&acc)[8][NNT], const LAS bf16_t* A, const int lda, const bf16_t* Bp, const int ldb) {
;     ...
; #pragma unroll
;     for (int mt = 0; mt < 8; ++mt) {
;         bf16x8 af[NKS];
; #pragma unroll
;         for (int ks = 0; ks < NKS; ++ks) af[ks] = *(const LAS bf16x8*)(A + (16 * mt) * lda + 32 * ks);
; #pragma unroll
;         for (int nt = 0; nt < NNT; ++nt) { f32x4 a = (f32x4){0.f, 0.f, 0.f, 0.f};
; #pragma unroll
;             for (int ks = 0; ks < NKS; ++ks) a = mfma16(as_bf16x8(bf[nt][ks]), af[ks], a);
;             acc[mt][nt] = a; }
;     }
; __device__ __forceinline__ void mixer_chunk(KP p, LAS unsigned char* lds, int l, int chunk) {
;     ...
;         if (w & 1) {
; #pragma unroll
;             for (int mt = 0; mt < 8; ++mt) { const float* rt = (const float*)(ws + OFF_ROPE) + (size_t)(c0 + 16 * mt + fr) * 32 + 4 * fq; csn[2 * mt] = *(const u32x4*)rt; csn[2 * mt + 1] = *(const u32x4*)(rt + 16); }
;             pin(csn);
;         }
	v_mfma_f32_16x16x32_bf16 v[26:29], v[2:5], v[172:175], v[26:29]
	v_mfma_f32_16x16x32_bf16 v[34:37], v[114:117], v[172:175], v[34:37]
	v_mfma_f32_16x16x32_bf16 v[42:45], v[134:137], v[172:175], v[10:13]
	ds_read_b128 v[18:21], v162 offset:38400
	ds_read_b128 v[158:161], v162 offset:38464
	ds_read_b128 v[172:175], v162 offset:38528
	ds_read_b128 v[176:179], v162 offset:38592
	ds_read_b128 v[180:183], v162 offset:38656
	ds_read_b128 v[184:187], v162 offset:38720
	s_waitcnt lgkmcnt(5)
	v_mfma_f32_16x16x32_bf16 v[10:13], v[154:157], v[18:21], 0
	v_mfma_f32_16x16x32_bf16 v[14:17], v[22:25], v[18:21], 0
	v_mfma_f32_16x16x32_bf16 v[18:21], v[146:149], v[18:21], 0
	s_waitcnt lgkmcnt(4)
	v_mfma_f32_16x16x32_bf16 v[10:13], v[150:153], v[158:161], v[10:13]
	v_mfma_f32_16x16x32_bf16 v[14:17], v[98:101], v[158:161], v[14:17]
	v_mfma_f32_16x16x32_bf16 v[18:21], v[118:121], v[158:161], v[18:21]
	s_waitcnt lgkmcnt(3)
	v_mfma_f32_16x16x32_bf16 v[10:13], v[142:145], v[172:175], v[10:13]
	v_mfma_f32_16x16x32_bf16 v[14:17], v[102:105], v[172:175], v[14:17]
	v_mfma_f32_16x16x32_bf16 v[18:21], v[122:125], v[172:175], v[18:21]
	s_waitcnt lgkmcnt(2)
	v_mfma_f32_16x16x32_bf16 v[10:13], v[138:141], v[176:179], v[10:13]
	v_mfma_f32_16x16x32_bf16 v[14:17], v[106:109], v[176:179], v[14:17]
	v_mfma_f32_16x16x32_bf16 v[18:21], v[126:129], v[176:179], v[18:21]
	s_waitcnt lgkmcnt(1)
	v_mfma_f32_16x16x32_bf16 v[10:13], v[6:9], v[180:183], v[10:13]
	v_mfma_f32_16x16x32_bf16 v[14:17], v[110:113], v[180:183], v[14:17]
	v_mfma_f32_16x16x32_bf16 v[18:21], v[130:133], v[180:183], v[18:21]
	s_waitcnt lgkmcnt(0)
	v_mfma_f32_16x16x32_bf16 v[10:13], v[2:5], v[184:187], v[10:13]
	v_mfma_f32_16x16x32_bf16 v[14:17], v[114:117], v[184:187], v[14:17]
	v_mfma_f32_16x16x32_bf16 v[18:21], v[134:137], v[184:187], v[18:21]
	ds_read_b128 v[158:161], v162 offset:44800
	ds_read_b128 v[172:175], v162 offset:44864
	ds_read_b128 v[176:179], v162 offset:44928
	ds_read_b128 v[180:183], v162 offset:44992
	ds_read_b128 v[184:187], v162 offset:45056
	ds_read_b128 v[226:229], v162 offset:45120
	s_waitcnt lgkmcnt(5)
	v_mfma_f32_16x16x32_bf16 v[154:157], v[154:157], v[158:161], 0
	s_waitcnt lgkmcnt(4)
	v_mfma_f32_16x16x32_bf16 v[150:153], v[150:153], v[172:175], v[154:157]
	s_waitcnt lgkmcnt(3)
	v_mfma_f32_16x16x32_bf16 v[142:145], v[142:145], v[176:179], v[150:153]
	s_waitcnt lgkmcnt(2)
	v_mfma_f32_16x16x32_bf16 v[138:141], v[138:141], v[180:183], v[142:145]
	s_waitcnt lgkmcnt(1)
	v_mfma_f32_16x16x32_bf16 v[6:9], v[6:9], v[184:187], v[138:141]
	s_waitcnt lgkmcnt(0)
	v_mfma_f32_16x16x32_bf16 v[2:5], v[2:5], v[226:229], v[6:9]
	v_mfma_f32_16x16x32_bf16 v[6:9], v[22:25], v[158:161], 0
	v_mfma_f32_16x16x32_bf16 v[22:25], v[146:149], v[158:161], 0
	v_mfma_f32_16x16x32_bf16 v[6:9], v[98:101], v[172:175], v[6:9]
	v_mfma_f32_16x16x32_bf16 v[22:25], v[118:121], v[172:175], v[22:25]
	v_or_b32_e32 v174, 0x60, v168
	v_or_b32_e32 v172, 0x70, v168
	v_mfma_f32_16x16x32_bf16 v[6:9], v[102:105], v[176:179], v[6:9]
	v_mfma_f32_16x16x32_bf16 v[22:25], v[122:125], v[176:179], v[22:25]
	v_or_b32_e32 v178, 64, v168
	v_or_b32_e32 v176, 0x50, v168
	v_mfma_f32_16x16x32_bf16 v[6:9], v[106:109], v[180:183], v[6:9]
	v_mfma_f32_16x16x32_bf16 v[22:25], v[126:129], v[180:183], v[22:25]
	v_or_b32_e32 v182, 32, v168
	v_or_b32_e32 v180, 48, v168
	v_mfma_f32_16x16x32_bf16 v[6:9], v[110:113], v[184:187], v[6:9]
	v_mfma_f32_16x16x32_bf16 v[22:25], v[130:133], v[184:187], v[22:25]
	v_or_b32_e32 v184, 16, v168
	v_mfma_f32_16x16x32_bf16 v[6:9], v[114:117], v[226:229], v[6:9]
	v_mfma_f32_16x16x32_bf16 v[22:25], v[134:137], v[226:229], v[22:25]
	s_cbranch_vccnz .LBB0_318
	v_lshlrev_b32_e32 v98, 2, v221
	v_mov_b32_e32 v99, v1
	v_lshl_add_u64 v[98:99], s[92:93], 0, v[98:99]
	v_lshlrev_b64 v[100:101], 7, v[168:169]
	v_lshl_add_u64 v[100:101], v[98:99], 0, v[100:101]
	v_ashrrev_i32_e32 v185, 31, v184
	global_load_dwordx4 v[158:161], v[100:101], off
	global_load_dwordx4 v[154:157], v[100:101], off offset:64
	v_lshlrev_b64 v[100:101], 7, v[184:185]
	v_lshl_add_u64 v[100:101], v[98:99], 0, v[100:101]
	v_ashrrev_i32_e32 v183, 31, v182
	global_load_dwordx4 v[150:153], v[100:101], off
	global_load_dwordx4 v[146:149], v[100:101], off offset:64
	v_lshlrev_b64 v[100:101], 7, v[182:183]
	v_lshl_add_u64 v[100:101], v[98:99], 0, v[100:101]
	v_ashrrev_i32_e32 v181, 31, v180
	global_load_dwordx4 v[142:145], v[100:101], off
	global_load_dwordx4 v[138:141], v[100:101], off offset:64
	v_lshlrev_b64 v[100:101], 7, v[180:181]
	v_lshl_add_u64 v[100:101], v[98:99], 0, v[100:101]
	v_ashrrev_i32_e32 v179, 31, v178
	global_load_dwordx4 v[134:137], v[100:101], off
	global_load_dwordx4 v[130:133], v[100:101], off offset:64
	v_lshlrev_b64 v[100:101], 7, v[178:179]
	v_lshl_add_u64 v[100:101], v[98:99], 0, v[100:101]
	v_ashrrev_i32_e32 v177, 31, v176
	global_load_dwordx4 v[126:129], v[100:101], off
	global_load_dwordx4 v[122:125], v[100:101], off offset:64
	v_lshlrev_b64 v[100:101], 7, v[176:177]
	v_lshl_add_u64 v[100:101], v[98:99], 0, v[100:101]
	v_ashrrev_i32_e32 v175, 31, v174
	global_load_dwordx4 v[118:121], v[100:101], off
	global_load_dwordx4 v[114:117], v[100:101], off offset:64
	v_lshlrev_b64 v[100:101], 7, v[174:175]
	v_lshl_add_u64 v[100:101], v[98:99], 0, v[100:101]
	v_ashrrev_i32_e32 v173, 31, v172
	global_load_dwordx4 v[110:113], v[100:101], off
	global_load_dwordx4 v[106:109], v[100:101], off offset:64
	v_lshlrev_b64 v[100:101], 7, v[172:173]
	v_lshl_add_u64 v[98:99], v[98:99], 0, v[100:101]
	global_load_dwordx4 v[102:105], v[98:99], off
	s_nop 0
	global_load_dwordx4 v[98:101], v[98:99], off offset:64
	s_waitcnt vmcnt(0)
; __device__ __forceinline__ unsigned pk2(float lo, float hi) { unsigned r; asm("v_cvt_pk_bf16_f32 %0, %1, %2" : "=v"(r) : "v"(lo), "v"(hi)); return r; }
; __device__ __forceinline__ void mixer_chunk(KP p, LAS unsigned char* lds, int l, int chunk) {
;     ...
; #pragma unroll
;         for (int mt = 0; mt < 8; ++mt) {
;             const float rs = RSQ[16 * mt + fr];
;             f32x4 a0 = acc[mt][0] * rs, a1 = acc[mt][1] * rs, a2 = acc[mt][2] * rs;
;             if (w & 1) { const f32x4 cs = __builtin_bit_cast(f32x4, csn[2 * mt]), sn = __builtin_bit_cast(f32x4, csn[2 * mt + 1]); const f32x4 x1 = a1, x2 = a2; a1 = x1 * cs - x2 * sn; a2 = x2 * cs + x1 * sn; }
;             bf16_t* qd = (bf16_t*)(ws + OFF_Q) + ((size_t)(bidx * 4 + head) * SEQ + s0 + 16 * mt + fr) * 96 + d0 + 4 * fq;
;             u32x2 o; o.x = pk2(a0[0], a0[1]); o.y = pk2(a0[2], a0[3]); *(u32x2*)(qd) = o;
;             o.x = pk2(a1[0], a1[1]); o.y = pk2(a1[2], a1[3]); *(u32x2*)(qd + 16) = o;
;             o.x = pk2(a2[0], a2[1]); o.y = pk2(a2[2], a2[3]); *(u32x2*)(qd + 32) = o;
;         }
.LBB0_318:
	s_mul_i32 s6, s55, 3
	s_lshr_b32 s7, s55, 31
	s_add_i32 s7, s55, s7
	s_mul_hi_i32 s18, s6, 0x2aaaaaab
	v_lshlrev_b32_e32 v169, 2, v217
	s_ashr_i32 s7, s7, 1
	s_lshr_b32 s58, s18, 31
	v_add_u32_e32 v162, 0, v169
	s_add_i32 s18, s18, s58
	v_add_u32_e32 v162, 0x15000, v162
	s_add_i32 s60, s7, s96
	s_mul_i32 s18, s18, 6
	s_ashr_i32 s61, s60, 31
	ds_read2_b32 v[226:227], v162 offset1:16
	s_sub_i32 s6, s6, s18
	s_lshl_b64 s[60:61], s[60:61], 12
	s_lshl_b32 s6, s6, 4
	s_or_b32 s7, s60, s24
	v_or_b32_e32 v163, s7, v217
	s_ashr_i32 s7, s6, 31
	s_lshl_b64 s[6:7], s[6:7], 1
	v_readlane_b32 s18, v252, 10
	s_add_u32 s6, s18, s6
	v_readlane_b32 s18, v252, 11
	s_waitcnt lgkmcnt(0)
	v_pk_mul_f32 v[230:231], v[82:83], v[226:227] op_sel_hi:[1,0]
	v_pk_mul_f32 v[82:83], v[92:93], v[226:227] op_sel_hi:[1,0]
	v_pk_mul_f32 v[90:91], v[90:91], v[226:227] op_sel_hi:[1,0]
	v_pk_mul_f32 v[92:93], v[96:97], v[226:227] op_sel_hi:[1,0]
	v_pk_mul_f32 v[94:95], v[94:95], v[226:227] op_sel_hi:[1,0]
	s_addc_u32 s7, s18, s7
	v_lshlrev_b32_e32 v186, 1, v221
	v_mov_b32_e32 v187, v1
	v_pk_mul_f32 v[96:97], v[154:155], v[94:95]
	v_pk_mul_f32 v[232:233], v[156:157], v[92:93]
	v_pk_mul_f32 v[154:155], v[154:155], v[90:91]
	v_lshl_add_u64 v[228:229], s[6:7], 0, v[186:187]
	v_pk_fma_f32 v[232:233], v[160:161], v[82:83], v[232:233] neg_lo:[0,0,1] neg_hi:[0,0,1]
	v_pk_fma_f32 v[154:155], v[158:159], v[94:95], v[154:155]
	v_pk_mul_f32 v[84:85], v[84:85], v[226:227] op_sel_hi:[1,0]
	v_pk_fma_f32 v[96:97], v[158:159], v[90:91], v[96:97] neg_lo:[0,0,1] neg_hi:[0,0,1]
	v_pk_mul_f32 v[156:157], v[156:157], v[82:83]
	v_cndmask_b32_e64 v94, v154, v94, s[42:43]
	v_cndmask_b32_e64 v95, v155, v95, s[42:43]
	v_cndmask_b32_e64 v154, v232, v82, s[42:43]
	v_cndmask_b32_e64 v155, v233, v83, s[42:43]
	v_mad_u64_u32 v[82:83], s[6:7], v163, s57, v[228:229]
	v_cndmask_b32_e64 v96, v96, v90, s[42:43]
	v_cndmask_b32_e64 v97, v97, v91, s[42:43]
	v_mad_i32_i24 v83, s61, v195, v83
	v_cvt_pk_bf16_f32 v91, v84, v85
	v_cvt_pk_bf16_f32 v84, v96, v97
	v_pk_fma_f32 v[156:157], v[160:161], v[92:93], v[156:157]
	v_cvt_pk_bf16_f32 v85, v154, v155
	s_nop 1
	v_mov_b32_e32 v244, v84
	v_mov_b32_e32 v245, v85
	v_cvt_pk_bf16_f32 v84, v94, v95
	v_cndmask_b32_e64 v92, v156, v92, s[42:43]
	v_cndmask_b32_e64 v93, v157, v93, s[42:43]
	v_cvt_pk_bf16_f32 v85, v92, v93
	v_mov_b32_e32 v246, v84
	v_mov_b32_e32 v247, v85
	v_bfe_u32 v248, v193, 4, 1
	v_mul_u32_u24_e32 v248, 24, v248
	v_add_co_u32_e64 v248, s[98:99], v248, v82
	s_nop 1
	v_addc_co_u32_e64 v249, s[98:99], 0, v83, s[98:99]
	v_permlane16_swap_b32_e32 v244, v246
	v_permlane16_swap_b32_e32 v245, v247
	global_store_dwordx4 v[248:249], v[244:247], off offset:32
	v_mov_b32_e32 v84, v227
	v_pk_mul_f32 v[76:77], v[76:77], v[84:85] op_sel_hi:[1,0]
	v_pk_mul_f32 v[74:75], v[74:75], v[84:85] op_sel_hi:[1,0]
	v_cvt_pk_bf16_f32 v90, v230, v231
	v_pk_mul_f32 v[80:81], v[80:81], v[84:85] op_sel_hi:[1,0]
	v_cvt_pk_bf16_f32 v74, v74, v75
	v_cvt_pk_bf16_f32 v75, v76, v77
	ds_read2_b32 v[76:77], v162 offset0:32 offset1:48
	v_pk_mul_f32 v[78:79], v[78:79], v[84:85] op_sel_hi:[1,0]
	v_pk_mul_f32 v[88:89], v[88:89], v[84:85] op_sel_hi:[1,0]
	v_pk_mul_f32 v[84:85], v[86:87], v[84:85] op_sel_hi:[1,0]
	global_store_dwordx2 v[82:83], v[90:91], off
	v_pk_mul_f32 v[86:87], v[146:147], v[84:85]
	v_pk_mul_f32 v[90:91], v[148:149], v[88:89]
	v_pk_fma_f32 v[86:87], v[150:151], v[78:79], v[86:87] neg_lo:[0,0,1] neg_hi:[0,0,1]
	v_pk_fma_f32 v[90:91], v[152:153], v[80:81], v[90:91] neg_lo:[0,0,1] neg_hi:[0,0,1]
	v_pk_mul_f32 v[92:93], v[146:147], v[78:79]
	v_pk_mul_f32 v[94:95], v[148:149], v[80:81]
	v_pk_fma_f32 v[92:93], v[150:151], v[84:85], v[92:93]
	v_pk_fma_f32 v[94:95], v[152:153], v[88:89], v[94:95]
	v_cndmask_b32_e64 v80, v90, v80, s[42:43]
	v_cndmask_b32_e64 v81, v91, v81, s[42:43]
	v_cndmask_b32_e64 v78, v86, v78, s[42:43]
	v_cndmask_b32_e64 v79, v87, v79, s[42:43]
	s_nop 1
	v_mov_b32_e32 v244, v74
	v_mov_b32_e32 v245, v75
	v_cvt_pk_bf16_f32 v74, v78, v79
	v_cvt_pk_bf16_f32 v75, v80, v81
	v_cndmask_b32_e64 v88, v94, v88, s[42:43]
	v_cndmask_b32_e64 v89, v95, v89, s[42:43]
	v_cndmask_b32_e64 v84, v92, v84, s[42:43]
	v_cndmask_b32_e64 v85, v93, v85, s[42:43]
	v_mov_b32_e32 v246, v74
	v_mov_b32_e32 v247, v75
	v_bfe_u32 v248, v193, 4, 1
	v_mul_u32_u24_e32 v248, 24, v248
	v_add_co_u32_e64 v248, s[98:99], v248, v82
	s_nop 1
	v_addc_co_u32_e64 v249, s[98:99], 0, v83, s[98:99]
	v_permlane16_swap_b32_e32 v244, v246
	v_permlane16_swap_b32_e32 v245, v247
	global_store_dwordx4 v[248:249], v[244:247], off offset:3072
	v_cvt_pk_bf16_f32 v74, v84, v85
	v_cvt_pk_bf16_f32 v75, v88, v89
	s_waitcnt lgkmcnt(0)
; __device__ __forceinline__ unsigned pk2(float lo, float hi) { unsigned r; asm("v_cvt_pk_bf16_f32 %0, %1, %2" : "=v"(r) : "v"(lo), "v"(hi)); return r; }
; __device__ __forceinline__ void mixer_chunk(KP p, LAS unsigned char* lds, int l, int chunk) {
;     ...
; #pragma unroll
;         for (int mt = 0; mt < 8; ++mt) {
;             const float rs = RSQ[16 * mt + fr];
;             f32x4 a0 = acc[mt][0] * rs, a1 = acc[mt][1] * rs, a2 = acc[mt][2] * rs;
;             if (w & 1) { const f32x4 cs = __builtin_bit_cast(f32x4, csn[2 * mt]), sn = __builtin_bit_cast(f32x4, csn[2 * mt + 1]); const f32x4 x1 = a1, x2 = a2; a1 = x1 * cs - x2 * sn; a2 = x2 * cs + x1 * sn; }
;             bf16_t* qd = (bf16_t*)(ws + OFF_Q) + ((size_t)(bidx * 4 + head) * SEQ + s0 + 16 * mt + fr) * 96 + d0 + 4 * fq;
;             u32x2 o; o.x = pk2(a0[0], a0[1]); o.y = pk2(a0[2], a0[3]); *(u32x2*)(qd) = o;
;             o.x = pk2(a1[0], a1[1]); o.y = pk2(a1[2], a1[3]); *(u32x2*)(qd + 16) = o;
;             o.x = pk2(a2[0], a2[1]); o.y = pk2(a2[2], a2[3]); *(u32x2*)(qd + 32) = o;
;         }
	v_pk_mul_f32 v[64:65], v[64:65], v[76:77] op_sel_hi:[1,0]
	v_pk_mul_f32 v[62:63], v[62:63], v[76:77] op_sel_hi:[1,0]
	v_pk_mul_f32 v[70:71], v[70:71], v[76:77] op_sel_hi:[1,0]
	s_movk_i32 s6, 0x1000
	global_store_dwordx2 v[82:83], v[74:75], off offset:3136
	v_pk_mul_f32 v[66:67], v[66:67], v[76:77] op_sel_hi:[1,0]
	v_pk_mul_f32 v[72:73], v[72:73], v[76:77] op_sel_hi:[1,0]
	v_pk_mul_f32 v[74:75], v[138:139], v[70:71]
	v_cvt_pk_bf16_f32 v62, v62, v63
	v_cvt_pk_bf16_f32 v63, v64, v65
	v_add_co_u32_e32 v64, vcc, s6, v82
	v_pk_mul_f32 v[68:69], v[68:69], v[76:77] op_sel_hi:[1,0]
	v_pk_mul_f32 v[78:79], v[140:141], v[72:73]
	v_pk_fma_f32 v[74:75], v[142:143], v[66:67], v[74:75] neg_lo:[0,0,1] neg_hi:[0,0,1]
	v_pk_mul_f32 v[80:81], v[138:139], v[66:67]
	v_addc_co_u32_e32 v65, vcc, 0, v83, vcc
	v_pk_fma_f32 v[78:79], v[144:145], v[68:69], v[78:79] neg_lo:[0,0,1] neg_hi:[0,0,1]
	v_pk_mul_f32 v[84:85], v[140:141], v[68:69]
	v_pk_fma_f32 v[80:81], v[142:143], v[70:71], v[80:81]
	v_cndmask_b32_e64 v66, v74, v66, s[42:43]
	v_cndmask_b32_e64 v67, v75, v67, s[42:43]
	s_nop 1
	v_mov_b32_e32 v244, v62
	v_mov_b32_e32 v245, v63
	v_cvt_pk_bf16_f32 v62, v66, v67
	v_pk_fma_f32 v[84:85], v[144:145], v[72:73], v[84:85]
	v_cndmask_b32_e64 v70, v80, v70, s[42:43]
	v_cndmask_b32_e64 v71, v81, v71, s[42:43]
	v_cndmask_b32_e64 v68, v78, v68, s[42:43]
	v_cndmask_b32_e64 v69, v79, v69, s[42:43]
	v_cvt_pk_bf16_f32 v63, v68, v69
	v_mov_b32_e32 v246, v62
	v_mov_b32_e32 v247, v63
	v_bfe_u32 v248, v193, 4, 1
	v_mul_u32_u24_e32 v248, 24, v248
	v_add_co_u32_e64 v248, s[98:99], v248, v64
	s_nop 1
	v_addc_co_u32_e64 v249, s[98:99], 0, v65, s[98:99]
	v_permlane16_swap_b32_e32 v244, v246
	v_permlane16_swap_b32_e32 v245, v247
	global_store_dwordx4 v[248:249], v[244:247], off offset:2048
	v_cvt_pk_bf16_f32 v62, v70, v71
	v_cndmask_b32_e64 v72, v84, v72, s[42:43]
	v_cndmask_b32_e64 v73, v85, v73, s[42:43]
	v_cvt_pk_bf16_f32 v63, v72, v73
	global_store_dwordx2 v[64:65], v[62:63], off offset:2112
	v_mov_b32_e32 v62, v77
	v_pk_mul_f32 v[58:59], v[58:59], v[62:63] op_sel_hi:[1,0]
	v_pk_mul_f32 v[52:53], v[52:53], v[62:63] op_sel_hi:[1,0]
	v_pk_mul_f32 v[50:51], v[50:51], v[62:63] op_sel_hi:[1,0]
	v_pk_mul_f32 v[56:57], v[56:57], v[62:63] op_sel_hi:[1,0]
	v_pk_mul_f32 v[54:55], v[54:55], v[62:63] op_sel_hi:[1,0]
	v_pk_mul_f32 v[60:61], v[60:61], v[62:63] op_sel_hi:[1,0]
	v_pk_mul_f32 v[62:63], v[130:131], v[58:59]
	v_cvt_pk_bf16_f32 v50, v50, v51
	v_cvt_pk_bf16_f32 v51, v52, v53
	v_add_co_u32_e32 v52, vcc, s39, v82
	v_pk_fma_f32 v[62:63], v[134:135], v[54:55], v[62:63] neg_lo:[0,0,1] neg_hi:[0,0,1]
	v_pk_mul_f32 v[66:67], v[130:131], v[54:55]
	v_cndmask_b32_e64 v54, v62, v54, s[42:43]
	v_cndmask_b32_e64 v55, v63, v55, s[42:43]
	v_addc_co_u32_e32 v53, vcc, 0, v83, vcc
	global_store_dwordx2 v[52:53], v[50:51], off offset:1024
	v_cvt_pk_bf16_f32 v50, v54, v55
	ds_read2_b32 v[54:55], v162 offset0:64 offset1:80
	v_pk_mul_f32 v[64:65], v[132:133], v[60:61]
	v_pk_mul_f32 v[68:69], v[132:133], v[56:57]
	v_pk_fma_f32 v[64:65], v[136:137], v[56:57], v[64:65] neg_lo:[0,0,1] neg_hi:[0,0,1]
	v_pk_fma_f32 v[68:69], v[136:137], v[60:61], v[68:69]
	v_pk_fma_f32 v[66:67], v[134:135], v[58:59], v[66:67]
	v_cndmask_b32_e64 v56, v64, v56, s[42:43]
	v_cndmask_b32_e64 v57, v65, v57, s[42:43]
	v_cvt_pk_bf16_f32 v51, v56, v57
	v_cndmask_b32_e64 v60, v68, v60, s[42:43]
	v_cndmask_b32_e64 v61, v69, v61, s[42:43]
	v_cndmask_b32_e64 v58, v66, v58, s[42:43]
	v_cndmask_b32_e64 v59, v67, v59, s[42:43]
	s_nop 1
	v_mov_b32_e32 v244, v50
	v_mov_b32_e32 v245, v51
	v_cvt_pk_bf16_f32 v50, v58, v59
	v_cvt_pk_bf16_f32 v51, v60, v61
	s_waitcnt lgkmcnt(0)
	v_pk_mul_f32 v[32:33], v[32:33], v[54:55] op_sel_hi:[1,0]
	v_pk_mul_f32 v[30:31], v[30:31], v[54:55] op_sel_hi:[1,0]
	v_pk_mul_f32 v[46:47], v[46:47], v[54:55] op_sel_hi:[1,0]
	v_mov_b32_e32 v246, v50
	v_mov_b32_e32 v247, v51
	v_bfe_u32 v248, v193, 4, 1
	v_mul_u32_u24_e32 v248, 24, v248
	v_add_co_u32_e64 v248, s[98:99], v248, v52
	s_nop 1
	v_addc_co_u32_e64 v249, s[98:99], 0, v53, s[98:99]
	v_permlane16_swap_b32_e32 v244, v246
	v_permlane16_swap_b32_e32 v245, v247
	global_store_dwordx4 v[248:249], v[244:247], off offset:1056
	v_pk_mul_f32 v[38:39], v[38:39], v[54:55] op_sel_hi:[1,0]
	v_pk_mul_f32 v[48:49], v[48:49], v[54:55] op_sel_hi:[1,0]
	v_pk_mul_f32 v[50:51], v[122:123], v[46:47]
	v_cvt_pk_bf16_f32 v30, v30, v31
	v_cvt_pk_bf16_f32 v31, v32, v33
	v_add_co_u32_e32 v32, vcc, s68, v82
	v_pk_mul_f32 v[40:41], v[40:41], v[54:55] op_sel_hi:[1,0]
	v_pk_mul_f32 v[52:53], v[124:125], v[48:49]
	v_pk_fma_f32 v[50:51], v[126:127], v[38:39], v[50:51] neg_lo:[0,0,1] neg_hi:[0,0,1]
	v_pk_mul_f32 v[56:57], v[122:123], v[38:39]
	v_addc_co_u32_e32 v33, vcc, 0, v83, vcc
	v_pk_fma_f32 v[52:53], v[128:129], v[40:41], v[52:53] neg_lo:[0,0,1] neg_hi:[0,0,1]
	v_pk_mul_f32 v[58:59], v[124:125], v[40:41]
	v_pk_fma_f32 v[56:57], v[126:127], v[46:47], v[56:57]
	v_cndmask_b32_e64 v38, v50, v38, s[42:43]
	v_cndmask_b32_e64 v39, v51, v39, s[42:43]
	s_nop 1
	v_mov_b32_e32 v244, v30
	v_mov_b32_e32 v245, v31
	v_cvt_pk_bf16_f32 v30, v38, v39
	v_pk_fma_f32 v[58:59], v[128:129], v[48:49], v[58:59]
	v_cndmask_b32_e64 v46, v56, v46, s[42:43]
	v_cndmask_b32_e64 v47, v57, v47, s[42:43]
	v_cndmask_b32_e64 v40, v52, v40, s[42:43]
	v_cndmask_b32_e64 v41, v53, v41, s[42:43]
	v_cvt_pk_bf16_f32 v31, v40, v41
	v_mov_b32_e32 v246, v30
	v_mov_b32_e32 v247, v31
	v_bfe_u32 v248, v193, 4, 1
	v_mul_u32_u24_e32 v248, 24, v248
	v_add_co_u32_e64 v248, s[98:99], v248, v32
	s_nop 1
	v_addc_co_u32_e64 v249, s[98:99], 0, v33, s[98:99]
	v_permlane16_swap_b32_e32 v244, v246
	v_permlane16_swap_b32_e32 v245, v247
; __device__ __forceinline__ unsigned pk2(float lo, float hi) { unsigned r; asm("v_cvt_pk_bf16_f32 %0, %1, %2" : "=v"(r) : "v"(lo), "v"(hi)); return r; }
; __device__ __forceinline__ void mixer_chunk(KP p, LAS unsigned char* lds, int l, int chunk) {
;     ...
; #pragma unroll
;         for (int mt = 0; mt < 8; ++mt) {
;             const float rs = RSQ[16 * mt + fr];
;             f32x4 a0 = acc[mt][0] * rs, a1 = acc[mt][1] * rs, a2 = acc[mt][2] * rs;
;             if (w & 1) { const f32x4 cs = __builtin_bit_cast(f32x4, csn[2 * mt]), sn = __builtin_bit_cast(f32x4, csn[2 * mt + 1]); const f32x4 x1 = a1, x2 = a2; a1 = x1 * cs - x2 * sn; a2 = x2 * cs + x1 * sn; }
;             bf16_t* qd = (bf16_t*)(ws + OFF_Q) + ((size_t)(bidx * 4 + head) * SEQ + s0 + 16 * mt + fr) * 96 + d0 + 4 * fq;
;             u32x2 o; o.x = pk2(a0[0], a0[1]); o.y = pk2(a0[2], a0[3]); *(u32x2*)(qd) = o;
;             o.x = pk2(a1[0], a1[1]); o.y = pk2(a1[2], a1[3]); *(u32x2*)(qd + 16) = o;
;             o.x = pk2(a2[0], a2[1]); o.y = pk2(a2[2], a2[3]); *(u32x2*)(qd + 32) = o;
;         }
	global_store_dwordx4 v[248:249], v[244:247], off
	v_cvt_pk_bf16_f32 v30, v46, v47
	v_cndmask_b32_e64 v48, v58, v48, s[42:43]
	v_cndmask_b32_e64 v49, v59, v49, s[42:43]
	v_cvt_pk_bf16_f32 v31, v48, v49
	global_store_dwordx2 v[32:33], v[30:31], off offset:64
	v_mov_b32_e32 v30, v55
	v_pk_mul_f32 v[28:29], v[28:29], v[30:31] op_sel_hi:[1,0]
	v_pk_mul_f32 v[26:27], v[26:27], v[30:31] op_sel_hi:[1,0]
	v_pk_mul_f32 v[36:37], v[36:37], v[30:31] op_sel_hi:[1,0]
	v_cvt_pk_bf16_f32 v26, v26, v27
	v_cvt_pk_bf16_f32 v27, v28, v29
	ds_read2_b32 v[28:29], v162 offset0:96 offset1:112
	v_pk_mul_f32 v[34:35], v[34:35], v[30:31] op_sel_hi:[1,0]
	v_pk_mul_f32 v[38:39], v[44:45], v[30:31] op_sel_hi:[1,0]
	v_pk_mul_f32 v[30:31], v[42:43], v[30:31] op_sel_hi:[1,0]
	v_pk_mul_f32 v[42:43], v[116:117], v[38:39]
	v_pk_mul_f32 v[40:41], v[114:115], v[30:31]
	v_pk_fma_f32 v[42:43], v[120:121], v[36:37], v[42:43] neg_lo:[0,0,1] neg_hi:[0,0,1]
	v_pk_fma_f32 v[40:41], v[118:119], v[34:35], v[40:41] neg_lo:[0,0,1] neg_hi:[0,0,1]
	v_pk_mul_f32 v[44:45], v[114:115], v[34:35]
	v_pk_mul_f32 v[46:47], v[116:117], v[36:37]
	v_pk_fma_f32 v[44:45], v[118:119], v[30:31], v[44:45]
	v_pk_fma_f32 v[46:47], v[120:121], v[38:39], v[46:47]
	v_cndmask_b32_e64 v36, v42, v36, s[42:43]
	v_cndmask_b32_e64 v37, v43, v37, s[42:43]
	v_cndmask_b32_e64 v34, v40, v34, s[42:43]
	v_cndmask_b32_e64 v35, v41, v35, s[42:43]
	s_nop 1
	v_mov_b32_e32 v244, v26
	v_mov_b32_e32 v245, v27
	v_cvt_pk_bf16_f32 v26, v34, v35
	v_cvt_pk_bf16_f32 v27, v36, v37
	v_cndmask_b32_e64 v38, v46, v38, s[42:43]
	v_cndmask_b32_e64 v39, v47, v39, s[42:43]
	v_cndmask_b32_e64 v30, v44, v30, s[42:43]
	v_cndmask_b32_e64 v31, v45, v31, s[42:43]
	v_mov_b32_e32 v246, v26
	v_mov_b32_e32 v247, v27
	v_bfe_u32 v248, v193, 4, 1
	v_mul_u32_u24_e32 v248, 24, v248
	v_add_co_u32_e64 v248, s[98:99], v248, v32
	s_nop 1
	v_addc_co_u32_e64 v249, s[98:99], 0, v33, s[98:99]
	v_permlane16_swap_b32_e32 v244, v246
	v_permlane16_swap_b32_e32 v245, v247
	global_store_dwordx4 v[248:249], v[244:247], off offset:3072
	v_cvt_pk_bf16_f32 v26, v30, v31
	v_cvt_pk_bf16_f32 v27, v38, v39
	s_waitcnt lgkmcnt(0)
	v_pk_mul_f32 v[12:13], v[12:13], v[28:29] op_sel_hi:[1,0]
	v_pk_mul_f32 v[10:11], v[10:11], v[28:29] op_sel_hi:[1,0]
	v_pk_mul_f32 v[18:19], v[18:19], v[28:29] op_sel_hi:[1,0]
	s_movk_i32 s6, 0x4000
	global_store_dwordx2 v[32:33], v[26:27], off offset:3136
	v_pk_mul_f32 v[14:15], v[14:15], v[28:29] op_sel_hi:[1,0]
	v_pk_mul_f32 v[20:21], v[20:21], v[28:29] op_sel_hi:[1,0]
	v_pk_mul_f32 v[26:27], v[106:107], v[18:19]
	v_cvt_pk_bf16_f32 v10, v10, v11
	v_cvt_pk_bf16_f32 v11, v12, v13
	v_add_co_u32_e32 v12, vcc, s6, v82
	v_pk_mul_f32 v[16:17], v[16:17], v[28:29] op_sel_hi:[1,0]
	v_pk_mul_f32 v[30:31], v[108:109], v[20:21]
	v_pk_fma_f32 v[26:27], v[110:111], v[14:15], v[26:27] neg_lo:[0,0,1] neg_hi:[0,0,1]
	v_pk_mul_f32 v[32:33], v[106:107], v[14:15]
	v_addc_co_u32_e32 v13, vcc, 0, v83, vcc
	v_pk_fma_f32 v[30:31], v[112:113], v[16:17], v[30:31] neg_lo:[0,0,1] neg_hi:[0,0,1]
	v_pk_mul_f32 v[34:35], v[108:109], v[16:17]
	v_pk_fma_f32 v[32:33], v[110:111], v[18:19], v[32:33]
	v_cndmask_b32_e64 v14, v26, v14, s[42:43]
	v_cndmask_b32_e64 v15, v27, v15, s[42:43]
	s_nop 1
	v_mov_b32_e32 v244, v10
	v_mov_b32_e32 v245, v11
	v_cvt_pk_bf16_f32 v10, v14, v15
	v_pk_fma_f32 v[34:35], v[112:113], v[20:21], v[34:35]
	v_cndmask_b32_e64 v18, v32, v18, s[42:43]
	v_cndmask_b32_e64 v19, v33, v19, s[42:43]
	v_cndmask_b32_e64 v16, v30, v16, s[42:43]
	v_cndmask_b32_e64 v17, v31, v17, s[42:43]
	v_cvt_pk_bf16_f32 v11, v16, v17
	v_mov_b32_e32 v246, v10
	v_mov_b32_e32 v247, v11
	v_bfe_u32 v248, v193, 4, 1
	v_mul_u32_u24_e32 v248, 24, v248
	v_add_co_u32_e64 v248, s[98:99], v248, v12
	s_nop 1
	v_addc_co_u32_e64 v249, s[98:99], 0, v13, s[98:99]
	v_permlane16_swap_b32_e32 v244, v246
	v_permlane16_swap_b32_e32 v245, v247
	global_store_dwordx4 v[248:249], v[244:247], off offset:2048
	v_cvt_pk_bf16_f32 v10, v18, v19
	v_cndmask_b32_e64 v20, v34, v20, s[42:43]
	v_cndmask_b32_e64 v21, v35, v21, s[42:43]
	v_cvt_pk_bf16_f32 v11, v20, v21
	global_store_dwordx2 v[12:13], v[10:11], off offset:2112
	v_mov_b32_e32 v10, v29
	v_pk_mul_f32 v[4:5], v[4:5], v[10:11] op_sel_hi:[1,0]
	v_pk_mul_f32 v[2:3], v[2:3], v[10:11] op_sel_hi:[1,0]
	v_pk_mul_f32 v[8:9], v[8:9], v[10:11] op_sel_hi:[1,0]
	v_pk_mul_f32 v[6:7], v[6:7], v[10:11] op_sel_hi:[1,0]
	v_pk_mul_f32 v[12:13], v[24:25], v[10:11] op_sel_hi:[1,0]
	v_pk_mul_f32 v[10:11], v[22:23], v[10:11] op_sel_hi:[1,0]
	s_movk_i32 s6, 0x5000
	v_pk_mul_f32 v[14:15], v[98:99], v[10:11]
	v_cvt_pk_bf16_f32 v2, v2, v3
	v_cvt_pk_bf16_f32 v3, v4, v5
	v_add_co_u32_e32 v4, vcc, s6, v82
; __device__ __forceinline__ unsigned pk2(float lo, float hi) { unsigned r; asm("v_cvt_pk_bf16_f32 %0, %1, %2" : "=v"(r) : "v"(lo), "v"(hi)); return r; }
; __device__ __forceinline__ void mixer_chunk(KP p, LAS unsigned char* lds, int l, int chunk) {
;     ...
;             u32x2 o; o.x = pk2(a0[0], a0[1]); o.y = pk2(a0[2], a0[3]); *(u32x2*)(qd) = o;
;             o.x = pk2(a1[0], a1[1]); o.y = pk2(a1[2], a1[3]); *(u32x2*)(qd + 16) = o;
;             o.x = pk2(a2[0], a2[1]); o.y = pk2(a2[2], a2[3]); *(u32x2*)(qd + 32) = o;
;         }
;     }
; #pragma unroll 1
;     for (int pz = 0; pz < 2; ++pz) {
;         f32x4 acc[8][2];
;         wgemm<4, 2>(acc, CK + fr * CKLD + 8 * fq, CKLD, (const bf16_t*)(ws + OFF_UKV + l * SZ_UKV) + (size_t)(64 * w + 32 * pz + fr) * 128 + 8 * fq, 128);
;         const int head = w >> 1;
; #pragma unroll
;         for (int mt = 0; mt < 8; ++mt) {
;             const float rs = RSK[16 * mt + fr]; const int spos = s0 + 16 * mt + fr;
; #pragma unroll
;             for (int n = 0; n < 2; ++n) {
;                 const f32x4 a = acc[mt][n] * rs; const unsigned p0 = pk2(a[0], a[1]), p1 = pk2(a[2], a[3]);
;                 if ((w & 1) == 0) { u32x2 o; o.x = p0; o.y = p1; *(u32x2*)((bf16_t*)(ws + OFF_K) + ((size_t)(bidx * 4 + head) * SEQ + spos) * 96 + 16 * (2 * pz + n) + 4 * fq) = o; }
;                 else { const int fp = ((fr & 4) << 1) | ((fr & 8) >> 1) | (fr & 3);
;                     bf16_t* vv = (bf16_t*)(ws + OFF_VT) + ((size_t)(bidx * 4 + head) * 64 + 16 * (2 * pz + n) + 4 * fq) * SEQ + (spos - fr + fp);
	v_pk_mul_f32 v[16:17], v[100:101], v[12:13]
	v_pk_fma_f32 v[14:15], v[102:103], v[6:7], v[14:15] neg_lo:[0,0,1] neg_hi:[0,0,1]
	v_pk_mul_f32 v[18:19], v[98:99], v[6:7]
	v_addc_co_u32_e32 v5, vcc, 0, v83, vcc
	v_pk_fma_f32 v[16:17], v[104:105], v[8:9], v[16:17] neg_lo:[0,0,1] neg_hi:[0,0,1]
	v_pk_mul_f32 v[20:21], v[100:101], v[8:9]
	v_pk_fma_f32 v[18:19], v[102:103], v[10:11], v[18:19]
	v_cndmask_b32_e64 v6, v14, v6, s[42:43]
	v_cndmask_b32_e64 v7, v15, v7, s[42:43]
	s_nop 1
	v_mov_b32_e32 v244, v2
	v_mov_b32_e32 v245, v3
	v_cvt_pk_bf16_f32 v2, v6, v7
	v_pk_fma_f32 v[20:21], v[104:105], v[12:13], v[20:21]
	v_cndmask_b32_e64 v10, v18, v10, s[42:43]
	v_cndmask_b32_e64 v11, v19, v11, s[42:43]
	v_cndmask_b32_e64 v8, v16, v8, s[42:43]
	v_cndmask_b32_e64 v9, v17, v9, s[42:43]
	v_cvt_pk_bf16_f32 v3, v8, v9
	v_mov_b32_e32 v246, v2
	v_mov_b32_e32 v247, v3
	v_bfe_u32 v248, v193, 4, 1
	v_mul_u32_u24_e32 v248, 24, v248
	v_add_co_u32_e64 v248, s[98:99], v248, v4
	s_nop 1
	v_addc_co_u32_e64 v249, s[98:99], 0, v5, s[98:99]
	v_permlane16_swap_b32_e32 v244, v246
	v_permlane16_swap_b32_e32 v245, v247
	global_store_dwordx4 v[248:249], v[244:247], off offset:1024
	v_cvt_pk_bf16_f32 v2, v10, v11
	v_cndmask_b32_e64 v12, v20, v12, s[42:43]
	v_cndmask_b32_e64 v13, v21, v13, s[42:43]
	v_cvt_pk_bf16_f32 v3, v12, v13
	global_store_dwordx2 v[4:5], v[2:3], off offset:1088
	v_mul_u32_u24_e32 v2, 0x110, v217
	v_add3_u32 v104, 0, v2, v0
	s_and_b32 s6, s54, 0xffffffc0
	v_lshlrev_b32_e32 v2, 1, v204
	v_lshrrev_b32_e32 v3, 1, v204
	v_or_b32_e32 v106, s6, v217
	s_add_i32 s6, 0, 0x15200
	v_and_b32_e32 v2, 8, v2
	v_and_b32_e32 v3, 4, v3
	v_and_b32_e32 v4, 3, v204
	v_add_u32_e32 v107, s6, v169
	s_add_i32 s6, s47, s96
	v_or3_b32 v6, v3, v4, v2
	s_ashr_i32 s7, s6, 31
	v_or_b32_e32 v4, s24, v6
	s_lshl_b64 s[42:43], s[6:7], 6
	s_lshl_b64 s[6:7], s[6:7], 12
	v_or_b32_e32 v7, s24, v217
	v_lshlrev_b32_e32 v4, 1, v4
	v_mov_b32_e32 v5, v1
	v_lshl_add_u64 v[2:3], s[12:13], 0, v[186:187]
	v_lshl_add_u64 v[66:67], s[8:9], 0, v[4:5]
	v_or_b32_e32 v4, s6, v7
	v_mov_b32_e32 v65, s43
	v_or_b32_e32 v64, s42, v221
	v_mad_u64_u32 v[68:69], s[42:43], v4, s57, v[2:3]
	s_or_b32 s42, s24, 16
	s_nop 0
	v_or_b32_e32 v4, s42, v217
	v_or_b32_e32 v4, s6, v4
	v_or_b32_e32 v5, s42, v6
	v_mad_u64_u32 v[70:71], s[42:43], v4, s57, v[2:3]
	s_or_b32 s42, s24, 32
	s_nop 0
	v_or_b32_e32 v4, s42, v217
	v_or_b32_e32 v4, s6, v4
	v_or_b32_e32 v7, s42, v6
	v_mad_u64_u32 v[72:73], s[42:43], v4, s57, v[2:3]
	s_or_b32 s42, s24, 48
	s_nop 0
	v_or_b32_e32 v4, s42, v217
	v_or_b32_e32 v4, s6, v4
	v_or_b32_e32 v8, s42, v6
	v_mad_u64_u32 v[74:75], s[42:43], v4, s57, v[2:3]
	s_or_b32 s42, s24, 64
	s_nop 0
	v_or_b32_e32 v4, s42, v217
	v_or_b32_e32 v4, s6, v4
	v_or_b32_e32 v9, s42, v6
	v_mad_u64_u32 v[76:77], s[42:43], v4, s57, v[2:3]
	s_or_b32 s42, s24, 0x50
	s_nop 0
	v_or_b32_e32 v4, s42, v217
	v_or_b32_e32 v4, s6, v4
	v_or_b32_e32 v10, s42, v6
	v_mad_u64_u32 v[78:79], s[42:43], v4, s57, v[2:3]
	s_or_b32 s42, s24, 0x60
	s_nop 0
	v_or_b32_e32 v4, s42, v217
	v_or_b32_e32 v4, s6, v4
	v_or_b32_e32 v11, s42, v6
	v_mad_u64_u32 v[80:81], s[42:43], v4, s57, v[2:3]
	s_or_b32 s42, s24, 0x70
	s_nop 0
	v_or_b32_e32 v4, s42, v217
	v_or_b32_e32 v4, s6, v4
	v_or_b32_e32 v6, s42, v6
	v_mad_u64_u32 v[82:83], s[42:43], v4, s57, v[2:3]
	v_lshlrev_b32_e32 v2, 1, v5
	v_mov_b32_e32 v3, v1
	v_lshl_add_u64 v[84:85], s[8:9], 0, v[2:3]
	v_lshlrev_b32_e32 v2, 1, v7
	v_lshl_add_u64 v[86:87], s[8:9], 0, v[2:3]
	v_lshlrev_b32_e32 v2, 1, v8
	v_lshl_add_u64 v[88:89], s[8:9], 0, v[2:3]
	v_lshlrev_b32_e32 v2, 1, v9
	v_lshl_add_u64 v[90:91], s[8:9], 0, v[2:3]
	v_lshlrev_b32_e32 v2, 1, v10
	v_lshl_add_u64 v[92:93], s[8:9], 0, v[2:3]
	v_lshlrev_b32_e32 v2, 1, v11
	v_lshl_add_u64 v[94:95], s[8:9], 0, v[2:3]
	v_lshlrev_b32_e32 v2, 1, v6
	s_mov_b32 s18, 0
	v_add_u32_e32 v105, 0xc800, v104
	v_lshl_add_u64 v[62:63], s[84:85], 0, v[0:1]
	v_mad_i32_i24 v69, s7, v195, v69
	v_mad_i32_i24 v71, s7, v195, v71
	v_mad_i32_i24 v73, s7, v195, v73
	v_mad_i32_i24 v75, s7, v195, v75
	v_mad_i32_i24 v77, s7, v195, v77
	v_mad_i32_i24 v79, s7, v195, v79
	v_mad_i32_i24 v81, s7, v195, v81
	v_mad_i32_i24 v83, s7, v195, v83
	v_lshl_add_u64 v[96:97], s[8:9], 0, v[2:3]
	s_mov_b64 s[96:97], -1
	s_branch .Lslack
	s_nop 0
	s_nop 0
	s_nop 0
	s_nop 0
	s_nop 0
	s_nop 0
	s_nop 0
	s_nop 0
	s_nop 0
	s_nop 0
	s_nop 0
	s_nop 0
	s_nop 0
	s_nop 0
	s_nop 0
	s_nop 0
	s_nop 0
	s_nop 0
	s_nop 0
	s_nop 0
	s_nop 0
	s_nop 0
	s_nop 0
	s_nop 0
	s_nop 0
	s_nop 0
	s_nop 0
	s_nop 0
	s_nop 0
.Lslack:
	s_branch .LBB0_320
.LBB0_319:
	s_xor_b64 s[6:7], s[96:97], -1
	s_mov_b32 s18, 32
	s_mov_b64 s[96:97], 0
	s_and_b64 vcc, exec, s[6:7]
	s_cbranch_vccnz .LBB0_384
